# attention: one workgroup barrier per two key tiles (ring slots written in an iteration were last read before the previous pair's barrier)
# baseline (speedup 1.0000x reference)
.Lat_qb:
	s_lshl_b32 s9, s2, 2
	s_lshr_b32 s10, s3, 1
	s_add_u32 s10, s10, s9
	s_add_u32 s11, s9, 3
	s_add_u32 s9, s9, 4
	s_lshl_b32 s18, s2, 8
	s_lshl_b32 s19, s3, 5
	s_add_u32 s18, s18, s19
	v_and_b32_e32 v235, 31, v186
	v_bfe_u32 v237, v186, 5, 1
	v_add_u32_e32 v235, s18, v235
	v_lshlrev_b32_e32 v219, 10, v235
	v_mul_u32_u24_e32 v236, 0x2cb0, v235
	v_lshl_add_u32 v220, v237, 4, v236
	v_lshl_add_u32 v197, v237, 3, v236
	global_load_dwordx4 v[102:105], v220, s[4:5] offset:0
	global_load_dwordx4 v[106:109], v220, s[4:5] offset:32
	global_load_dwordx4 v[110:113], v220, s[4:5] offset:64
	global_load_dwordx4 v[114:117], v220, s[4:5] offset:96
	s_mov_b64 s[12:13], s[4:5]
	s_add_i32 m0, s58, 0x0
	s_nop 0
	global_load_lds_dwordx4 v221, s[12:13]
	s_add_i32 m0, s58, 0x8000
	s_nop 0
	global_load_lds_dwordx4 v222, s[12:13]
	s_add_u32 s12, s12, 0xb2c00
	s_addc_u32 s13, s13, 0
	s_add_i32 m0, s58, 0x2000
	s_nop 0
	global_load_lds_dwordx4 v221, s[12:13]
	s_add_u32 s12, s12, 0xb2c00
	s_addc_u32 s13, s13, 0
	s_add_i32 m0, s58, 0x4000
	s_nop 0
	global_load_lds_dwordx4 v221, s[12:13]
	s_add_u32 s12, s12, 0xb2c00
	s_addc_u32 s13, s13, 0
	global_load_dwordx4 v[198:201], v219, s[6:7]
	s_add_i32 m0, s58, 0x6000
	s_nop 0
	global_load_lds_dwordx4 v221, s[12:13]
	s_add_u32 s14, s4, 0xb2c00
	s_addc_u32 s15, s5, 0
	s_add_i32 m0, s58, 0xa000
	s_nop 0
	global_load_lds_dwordx4 v222, s[14:15]
	v_mov_b32_e32 v230, 0xff800000
	v_mov_b32_e32 v231, 0
	v_mov_b32_e32 v0, 0
	v_mov_b32_e32 v1, 0
	v_mov_b32_e32 v2, 0
	v_mov_b32_e32 v3, 0
	v_mov_b32_e32 v4, 0
	v_mov_b32_e32 v5, 0
	v_mov_b32_e32 v6, 0
	v_mov_b32_e32 v7, 0
	v_mov_b32_e32 v8, 0
	v_mov_b32_e32 v9, 0
	v_mov_b32_e32 v10, 0
	v_mov_b32_e32 v11, 0
	v_mov_b32_e32 v12, 0
	v_mov_b32_e32 v13, 0
	v_mov_b32_e32 v14, 0
	v_mov_b32_e32 v15, 0
	v_mov_b32_e32 v16, 0
	v_mov_b32_e32 v17, 0
	v_mov_b32_e32 v18, 0
	v_mov_b32_e32 v19, 0
	v_mov_b32_e32 v20, 0
	v_mov_b32_e32 v21, 0
	v_mov_b32_e32 v22, 0
	v_mov_b32_e32 v23, 0
	v_mov_b32_e32 v24, 0
	v_mov_b32_e32 v25, 0
	v_mov_b32_e32 v26, 0
	v_mov_b32_e32 v27, 0
	v_mov_b32_e32 v28, 0
	v_mov_b32_e32 v29, 0
	v_mov_b32_e32 v30, 0
	v_mov_b32_e32 v31, 0
	s_waitcnt vmcnt(0)
	s_barrier
	ds_read_b128 v[118:121], v223 offset:0
	ds_read_b128 v[122:125], v223 offset:4096
	ds_read_b128 v[126:129], v224 offset:0
	ds_read_b128 v[130:133], v224 offset:4096
	ds_read_b128 v[134:137], v225 offset:0
	ds_read_b128 v[138:141], v225 offset:4096
	ds_read_b128 v[142:145], v226 offset:0
	ds_read_b128 v[146:149], v226 offset:4096
	s_waitcnt lgkmcnt(0)
	s_barrier
	v_mfma_f32_32x32x16_bf16 v[34:49], v[118:121], v[102:105], 0
	v_mfma_f32_32x32x16_bf16 v[50:65], v[122:125], v[102:105], 0
	v_mfma_f32_32x32x16_bf16 v[34:49], v[126:129], v[106:109], v[34:49]
	v_mfma_f32_32x32x16_bf16 v[50:65], v[130:133], v[106:109], v[50:65]
	v_mfma_f32_32x32x16_bf16 v[34:49], v[134:137], v[110:113], v[34:49]
	v_mfma_f32_32x32x16_bf16 v[50:65], v[138:141], v[110:113], v[50:65]
	v_mfma_f32_32x32x16_bf16 v[34:49], v[142:145], v[114:117], v[34:49]
	v_mfma_f32_32x32x16_bf16 v[50:65], v[146:149], v[114:117], v[50:65]
	ds_read_b128 v[118:121], v223 offset:8192
	ds_read_b128 v[122:125], v223 offset:12288
	ds_read_b128 v[126:129], v224 offset:8192
	ds_read_b128 v[130:133], v224 offset:12288
	ds_read_b128 v[134:137], v225 offset:8192
	ds_read_b128 v[138:141], v225 offset:12288
	ds_read_b128 v[142:145], v226 offset:8192
	ds_read_b128 v[146:149], v226 offset:12288
	s_waitcnt lgkmcnt(14)
	s_mov_b32 s8, 0
	s_nop 7
	v_lshrrev_b32_e32 v249, v229, v198
	v_lshrrev_b32_e32 v250, v229, v199
	v_bfe_i32 v235, v249, 0, 1
	v_bfe_i32 v236, v250, 0, 1
	v_bfe_i32 v237, v249, 1, 1
	v_bfe_i32 v238, v250, 1, 1
	v_bfe_i32 v239, v249, 2, 1
	v_bfe_i32 v240, v250, 2, 1
	v_bfe_i32 v241, v249, 3, 1
	v_bfe_i32 v242, v250, 3, 1
	v_bitop3_b32 v34, v34, s33, v235 bitop3:0xe4
	v_bitop3_b32 v50, v50, s33, v236 bitop3:0xe4
	v_bitop3_b32 v35, v35, s33, v237 bitop3:0xe4
	v_bitop3_b32 v51, v51, s33, v238 bitop3:0xe4
	v_bitop3_b32 v36, v36, s33, v239 bitop3:0xe4
	v_bitop3_b32 v52, v52, s33, v240 bitop3:0xe4
	v_bitop3_b32 v37, v37, s33, v241 bitop3:0xe4
	v_bitop3_b32 v53, v53, s33, v242 bitop3:0xe4
	v_max3_f32 v247, v34, s33, v50
	v_max3_f32 v248, v35, s33, v51
	v_max3_f32 v247, v247, v36, v52
	v_max3_f32 v248, v248, v37, v53
	v_bfe_i32 v235, v249, 8, 1
	v_bfe_i32 v236, v250, 8, 1
	v_bfe_i32 v237, v249, 9, 1
	v_bfe_i32 v238, v250, 9, 1
	v_bfe_i32 v239, v249, 10, 1
	v_bfe_i32 v240, v250, 10, 1
	v_bfe_i32 v241, v249, 11, 1
	v_bfe_i32 v242, v250, 11, 1
	v_bitop3_b32 v38, v38, s33, v235 bitop3:0xe4
	v_bitop3_b32 v54, v54, s33, v236 bitop3:0xe4
	v_bitop3_b32 v39, v39, s33, v237 bitop3:0xe4
	v_bitop3_b32 v55, v55, s33, v238 bitop3:0xe4
	v_bitop3_b32 v40, v40, s33, v239 bitop3:0xe4
	v_bitop3_b32 v56, v56, s33, v240 bitop3:0xe4
	v_bitop3_b32 v41, v41, s33, v241 bitop3:0xe4
	v_bitop3_b32 v57, v57, s33, v242 bitop3:0xe4
	v_max3_f32 v247, v247, v38, v54
	v_max3_f32 v248, v248, v39, v55
	v_max3_f32 v247, v247, v40, v56
	v_max3_f32 v248, v248, v41, v57
	v_bfe_i32 v235, v249, 16, 1
	v_bfe_i32 v236, v250, 16, 1
	v_bfe_i32 v237, v249, 17, 1
	v_bfe_i32 v238, v250, 17, 1
	v_bfe_i32 v239, v249, 18, 1
	v_bfe_i32 v240, v250, 18, 1
	v_bfe_i32 v241, v249, 19, 1
	v_bfe_i32 v242, v250, 19, 1
	v_bitop3_b32 v42, v42, s33, v235 bitop3:0xe4
	v_bitop3_b32 v58, v58, s33, v236 bitop3:0xe4
	v_bitop3_b32 v43, v43, s33, v237 bitop3:0xe4
	v_bitop3_b32 v59, v59, s33, v238 bitop3:0xe4
	v_bitop3_b32 v44, v44, s33, v239 bitop3:0xe4
	v_bitop3_b32 v60, v60, s33, v240 bitop3:0xe4
	v_bitop3_b32 v45, v45, s33, v241 bitop3:0xe4
	v_bitop3_b32 v61, v61, s33, v242 bitop3:0xe4
	v_max3_f32 v247, v247, v42, v58
	v_max3_f32 v248, v248, v43, v59
	v_max3_f32 v247, v247, v44, v60
	v_max3_f32 v248, v248, v45, v61
	v_bfe_i32 v235, v249, 24, 1
	v_bfe_i32 v236, v250, 24, 1
	v_bfe_i32 v237, v249, 25, 1
	v_bfe_i32 v238, v250, 25, 1
	v_bfe_i32 v239, v249, 26, 1
	v_bfe_i32 v240, v250, 26, 1
	v_bfe_i32 v241, v249, 27, 1
	v_bfe_i32 v242, v250, 27, 1
	v_bitop3_b32 v46, v46, s33, v235 bitop3:0xe4
	v_bitop3_b32 v62, v62, s33, v236 bitop3:0xe4
	v_bitop3_b32 v47, v47, s33, v237 bitop3:0xe4
	v_bitop3_b32 v63, v63, s33, v238 bitop3:0xe4
	v_bitop3_b32 v48, v48, s33, v239 bitop3:0xe4
	v_bitop3_b32 v64, v64, s33, v240 bitop3:0xe4
	v_bitop3_b32 v49, v49, s33, v241 bitop3:0xe4
	v_bitop3_b32 v65, v65, s33, v242 bitop3:0xe4
	v_max3_f32 v247, v247, v46, v62
	v_max3_f32 v248, v248, v47, v63
	v_max3_f32 v247, v247, v48, v64
	v_max3_f32 v248, v248, v49, v65
	v_max_f32_e32 v247, v247, v248
	v_mov_b32_e32 v248, v247
	s_nop 1
	v_permlane32_swap_b32_e32 v247, v248
	v_max3_f32 v247, v230, v247, v248
	v_cmp_neq_f32_e32 vcc, s33, v247
	s_nop 1
	v_cndmask_b32_e32 v248, 0, v247, vcc
	v_sub_f32_e32 v33, v230, v248
	v_mul_f32_e32 v33, 0x3e38aa3b, v33
	v_exp_f32_e32 v232, v33
	v_mul_f32_e32 v234, 0xbe38aa3b, v248
	v_mov_b32_e32 v230, v247

.Lat_idle_0:
	s_add_u32 s8, s8, 1
	s_cmp_lt_u32 s8, s9
	s_cbranch_scc1 .Lat_loop_1
	s_branch .Lat_epilogue

.Lat_nors_f0:
	v_fmamk_f32 v34, v34, 0x3e38aa3b, v234
	v_fmamk_f32 v35, v35, 0x3e38aa3b, v234
	s_waitcnt lgkmcnt(7)
	v_mfma_f32_32x32x16_bf16 v[70:85], v[118:121], v[102:105], 0
	ds_read_b64_tr_b16 v[154:155], v227 offset:0
	ds_read_b64_tr_b16 v[156:157], v227 offset:1024
	v_fmamk_f32 v36, v36, 0x3e38aa3b, v234
	v_fmamk_f32 v37, v37, 0x3e38aa3b, v234
	v_fmamk_f32 v38, v38, 0x3e38aa3b, v234
	v_fmamk_f32 v39, v39, 0x3e38aa3b, v234
	v_fmamk_f32 v40, v40, 0x3e38aa3b, v234
	v_fmamk_f32 v41, v41, 0x3e38aa3b, v234
	v_exp_f32_e32 v34, v34
	v_exp_f32_e32 v35, v35
	v_exp_f32_e32 v36, v36
	v_exp_f32_e32 v37, v37
	v_exp_f32_e32 v38, v38
	v_exp_f32_e32 v39, v39
	s_waitcnt lgkmcnt(8)
	v_mfma_f32_32x32x16_bf16 v[86:101], v[122:125], v[102:105], 0
	ds_read_b64_tr_b16 v[158:159], v228 offset:0
	ds_read_b64_tr_b16 v[160:161], v228 offset:1024
	v_exp_f32_e32 v40, v40
	v_exp_f32_e32 v41, v41
	v_add_f32_e32 v243, v34, v38
	v_add_f32_e32 v244, v35, v39
	v_add_f32_e32 v245, v36, v40
	v_add_f32_e32 v246, v37, v41
	v_cvt_pk_bf16_f32 v34, v34, v35
	v_cvt_pk_bf16_f32 v35, v36, v37
	v_cvt_pk_bf16_f32 v36, v38, v39
	v_cvt_pk_bf16_f32 v37, v40, v41
	v_fmamk_f32 v42, v42, 0x3e38aa3b, v234
	v_fmamk_f32 v43, v43, 0x3e38aa3b, v234
	s_waitcnt lgkmcnt(9)
	v_mfma_f32_32x32x16_bf16 v[70:85], v[126:129], v[106:109], v[70:85]
	ds_read_b64_tr_b16 v[162:163], v227 offset:2048
	ds_read_b64_tr_b16 v[164:165], v227 offset:3072
	v_fmamk_f32 v44, v44, 0x3e38aa3b, v234
	v_fmamk_f32 v45, v45, 0x3e38aa3b, v234
	v_fmamk_f32 v46, v46, 0x3e38aa3b, v234
	v_fmamk_f32 v47, v47, 0x3e38aa3b, v234
	v_fmamk_f32 v48, v48, 0x3e38aa3b, v234
	v_fmamk_f32 v49, v49, 0x3e38aa3b, v234
	v_exp_f32_e32 v42, v42
	v_exp_f32_e32 v43, v43
	v_exp_f32_e32 v44, v44
	v_exp_f32_e32 v45, v45
	v_exp_f32_e32 v46, v46
	v_exp_f32_e32 v47, v47
	s_waitcnt lgkmcnt(10)
	v_mfma_f32_32x32x16_bf16 v[86:101], v[130:133], v[106:109], v[86:101]
	ds_read_b64_tr_b16 v[166:167], v228 offset:2048
	ds_read_b64_tr_b16 v[168:169], v228 offset:3072
	v_exp_f32_e32 v48, v48
	v_exp_f32_e32 v49, v49
	v_add_f32_e32 v243, v243, v42
	v_add_f32_e32 v244, v244, v43
	v_add_f32_e32 v245, v245, v44
	v_add_f32_e32 v246, v246, v45
	v_add_f32_e32 v243, v243, v46
	v_add_f32_e32 v244, v244, v47
	v_add_f32_e32 v245, v245, v48
	v_add_f32_e32 v246, v246, v49
	v_cvt_pk_bf16_f32 v42, v42, v43
	v_cvt_pk_bf16_f32 v43, v44, v45
	s_waitcnt lgkmcnt(11)
	v_mfma_f32_32x32x16_bf16 v[70:85], v[134:137], v[110:113], v[70:85]
	ds_read_b64_tr_b16 v[170:171], v227 offset:4096
	ds_read_b64_tr_b16 v[172:173], v227 offset:5120
	v_cvt_pk_bf16_f32 v44, v46, v47
	v_cvt_pk_bf16_f32 v45, v48, v49
	v_fmamk_f32 v50, v50, 0x3e38aa3b, v234
	v_fmamk_f32 v51, v51, 0x3e38aa3b, v234
	v_fmamk_f32 v52, v52, 0x3e38aa3b, v234
	v_fmamk_f32 v53, v53, 0x3e38aa3b, v234
	v_fmamk_f32 v54, v54, 0x3e38aa3b, v234
	v_fmamk_f32 v55, v55, 0x3e38aa3b, v234
	v_fmamk_f32 v56, v56, 0x3e38aa3b, v234
	v_fmamk_f32 v57, v57, 0x3e38aa3b, v234
	v_exp_f32_e32 v50, v50
	v_exp_f32_e32 v51, v51
	s_waitcnt lgkmcnt(12)
	v_mfma_f32_32x32x16_bf16 v[86:101], v[138:141], v[110:113], v[86:101]
	ds_read_b64_tr_b16 v[174:175], v228 offset:4096
	ds_read_b64_tr_b16 v[176:177], v228 offset:5120
	v_exp_f32_e32 v52, v52
	v_exp_f32_e32 v53, v53
	v_exp_f32_e32 v54, v54
	v_exp_f32_e32 v55, v55
	v_exp_f32_e32 v56, v56
	v_exp_f32_e32 v57, v57
	v_add_f32_e32 v243, v243, v50
	v_add_f32_e32 v244, v244, v51
	v_add_f32_e32 v245, v245, v52
	v_add_f32_e32 v246, v246, v53
	v_add_f32_e32 v243, v243, v54
	v_add_f32_e32 v244, v244, v55
	s_waitcnt lgkmcnt(13)
	v_mfma_f32_32x32x16_bf16 v[70:85], v[142:145], v[114:117], v[70:85]
	ds_read_b64_tr_b16 v[178:179], v227 offset:6144
	ds_read_b64_tr_b16 v[180:181], v227 offset:7168
	v_add_f32_e32 v245, v245, v56
	v_add_f32_e32 v246, v246, v57
	v_cvt_pk_bf16_f32 v50, v50, v51
	v_cvt_pk_bf16_f32 v51, v52, v53
	v_cvt_pk_bf16_f32 v52, v54, v55
	v_cvt_pk_bf16_f32 v53, v56, v57
	v_fmamk_f32 v58, v58, 0x3e38aa3b, v234
	v_fmamk_f32 v59, v59, 0x3e38aa3b, v234
	v_fmamk_f32 v60, v60, 0x3e38aa3b, v234
	v_fmamk_f32 v61, v61, 0x3e38aa3b, v234
	v_fmamk_f32 v62, v62, 0x3e38aa3b, v234
	v_fmamk_f32 v63, v63, 0x3e38aa3b, v234
	s_waitcnt lgkmcnt(14)
	v_mfma_f32_32x32x16_bf16 v[86:101], v[146:149], v[114:117], v[86:101]
	ds_read_b64_tr_b16 v[182:183], v228 offset:6144
	ds_read_b64_tr_b16 v[184:185], v228 offset:7168
	s_waitcnt lgkmcnt(14)
	v_fmamk_f32 v64, v64, 0x3e38aa3b, v234
	v_fmamk_f32 v65, v65, 0x3e38aa3b, v234
	v_exp_f32_e32 v58, v58
	v_exp_f32_e32 v59, v59
	v_exp_f32_e32 v60, v60
	v_exp_f32_e32 v61, v61
	v_exp_f32_e32 v62, v62
	v_exp_f32_e32 v63, v63
	v_exp_f32_e32 v64, v64
	v_exp_f32_e32 v65, v65
	v_add_f32_e32 v243, v243, v58
	v_add_f32_e32 v244, v244, v59
	v_add_f32_e32 v245, v245, v60
	v_add_f32_e32 v246, v246, v61
	s_waitcnt lgkmcnt(14)
	v_mfma_f32_32x32x16_bf16 v[0:15], v[154:157], v[34:37], v[0:15]
	ds_read_b128 v[118:121], v223 offset:16384
	v_add_f32_e32 v243, v243, v62
	v_add_f32_e32 v244, v244, v63
	v_add_f32_e32 v245, v245, v64
	v_add_f32_e32 v246, v246, v65
	v_cvt_pk_bf16_f32 v58, v58, v59
	v_cvt_pk_bf16_f32 v59, v60, v61
	v_cvt_pk_bf16_f32 v60, v62, v63
	v_cvt_pk_bf16_f32 v61, v64, v65
	v_add_f32_e32 v243, v243, v244
	v_add_f32_e32 v245, v245, v246
	v_add_f32_e32 v243, v243, v245
	v_fma_f32 v231, v231, v232, v243
	s_waitcnt lgkmcnt(13)
	v_mfma_f32_32x32x16_bf16 v[16:31], v[158:161], v[34:37], v[16:31]
	ds_read_b128 v[122:125], v223 offset:20480
	v_lshrrev_b32_e32 v249, v229, v200
	v_lshrrev_b32_e32 v250, v229, v201
	v_bfe_i32 v235, v249, 0, 1
	v_bfe_i32 v236, v250, 0, 1
	v_bfe_i32 v237, v249, 1, 1
	v_bfe_i32 v238, v250, 1, 1
	v_bfe_i32 v239, v249, 2, 1
	v_bfe_i32 v240, v250, 2, 1
	v_bfe_i32 v241, v249, 3, 1
	v_bfe_i32 v242, v250, 3, 1
	v_bitop3_b32 v70, v70, s33, v235 bitop3:0xe4
	s_waitcnt lgkmcnt(12)
	v_mfma_f32_32x32x16_bf16 v[0:15], v[162:165], v[42:45], v[0:15]
	ds_read_b128 v[126:129], v224 offset:16384
	v_bitop3_b32 v86, v86, s33, v236 bitop3:0xe4
	v_bitop3_b32 v71, v71, s33, v237 bitop3:0xe4
	v_bitop3_b32 v87, v87, s33, v238 bitop3:0xe4
	v_bitop3_b32 v72, v72, s33, v239 bitop3:0xe4
	v_bitop3_b32 v88, v88, s33, v240 bitop3:0xe4
	v_bitop3_b32 v73, v73, s33, v241 bitop3:0xe4
	v_bitop3_b32 v89, v89, s33, v242 bitop3:0xe4
	v_max3_f32 v247, v70, s33, v86
	v_max3_f32 v248, v71, s33, v87
	v_max3_f32 v247, v247, v72, v88
	v_max3_f32 v248, v248, v73, v89
	v_bfe_i32 v235, v249, 8, 1
	s_waitcnt lgkmcnt(11)
	v_mfma_f32_32x32x16_bf16 v[16:31], v[166:169], v[42:45], v[16:31]
	ds_read_b128 v[130:133], v224 offset:20480
	v_bfe_i32 v236, v250, 8, 1
	v_bfe_i32 v237, v249, 9, 1
	v_bfe_i32 v238, v250, 9, 1
	v_bfe_i32 v239, v249, 10, 1
	v_bfe_i32 v240, v250, 10, 1
	v_bfe_i32 v241, v249, 11, 1
	v_bfe_i32 v242, v250, 11, 1
	v_bitop3_b32 v74, v74, s33, v235 bitop3:0xe4
	v_bitop3_b32 v90, v90, s33, v236 bitop3:0xe4
	v_bitop3_b32 v75, v75, s33, v237 bitop3:0xe4
	v_bitop3_b32 v91, v91, s33, v238 bitop3:0xe4
	v_bitop3_b32 v76, v76, s33, v239 bitop3:0xe4
	s_waitcnt lgkmcnt(10)
	v_mfma_f32_32x32x16_bf16 v[0:15], v[170:173], v[50:53], v[0:15]
	ds_read_b128 v[134:137], v225 offset:16384
	v_bitop3_b32 v92, v92, s33, v240 bitop3:0xe4
	v_bitop3_b32 v77, v77, s33, v241 bitop3:0xe4
	v_bitop3_b32 v93, v93, s33, v242 bitop3:0xe4
	v_max3_f32 v247, v247, v74, v90
	v_max3_f32 v248, v248, v75, v91
	v_max3_f32 v247, v247, v76, v92
	v_max3_f32 v248, v248, v77, v93
	v_bfe_i32 v235, v249, 16, 1
	v_bfe_i32 v236, v250, 16, 1
	v_bfe_i32 v237, v249, 17, 1
	v_bfe_i32 v238, v250, 17, 1
	v_bfe_i32 v239, v249, 18, 1
	s_waitcnt lgkmcnt(9)
	v_mfma_f32_32x32x16_bf16 v[16:31], v[174:177], v[50:53], v[16:31]
	ds_read_b128 v[138:141], v225 offset:20480
	v_bfe_i32 v240, v250, 18, 1
	v_bfe_i32 v241, v249, 19, 1
	v_bfe_i32 v242, v250, 19, 1
	v_bitop3_b32 v78, v78, s33, v235 bitop3:0xe4
	v_bitop3_b32 v94, v94, s33, v236 bitop3:0xe4
	v_bitop3_b32 v79, v79, s33, v237 bitop3:0xe4
	v_bitop3_b32 v95, v95, s33, v238 bitop3:0xe4
	v_bitop3_b32 v80, v80, s33, v239 bitop3:0xe4
	v_bitop3_b32 v96, v96, s33, v240 bitop3:0xe4
	v_bitop3_b32 v81, v81, s33, v241 bitop3:0xe4
	v_bitop3_b32 v97, v97, s33, v242 bitop3:0xe4
	v_max3_f32 v247, v247, v78, v94
	s_waitcnt lgkmcnt(8)
	v_mfma_f32_32x32x16_bf16 v[0:15], v[178:181], v[58:61], v[0:15]
	ds_read_b128 v[142:145], v226 offset:16384
	v_max3_f32 v248, v248, v79, v95
	v_max3_f32 v247, v247, v80, v96
	v_max3_f32 v248, v248, v81, v97
	v_bfe_i32 v235, v249, 24, 1
	v_bfe_i32 v236, v250, 24, 1
	v_bfe_i32 v237, v249, 25, 1
	v_bfe_i32 v238, v250, 25, 1
	v_bfe_i32 v239, v249, 26, 1
	v_bfe_i32 v240, v250, 26, 1
	v_bfe_i32 v241, v249, 27, 1
	v_bfe_i32 v242, v250, 27, 1
	v_bitop3_b32 v82, v82, s33, v235 bitop3:0xe4
	s_waitcnt lgkmcnt(7)
	v_mfma_f32_32x32x16_bf16 v[16:31], v[182:185], v[58:61], v[16:31]
	ds_read_b128 v[146:149], v226 offset:20480
	v_bitop3_b32 v98, v98, s33, v236 bitop3:0xe4
	v_bitop3_b32 v83, v83, s33, v237 bitop3:0xe4
	v_bitop3_b32 v99, v99, s33, v238 bitop3:0xe4
	v_bitop3_b32 v84, v84, s33, v239 bitop3:0xe4
	v_bitop3_b32 v100, v100, s33, v240 bitop3:0xe4
	v_bitop3_b32 v85, v85, s33, v241 bitop3:0xe4
	v_bitop3_b32 v101, v101, s33, v242 bitop3:0xe4
	v_max3_f32 v247, v247, v82, v98
	v_max3_f32 v248, v248, v83, v99
	v_max3_f32 v247, v247, v84, v100
	v_max3_f32 v248, v248, v85, v101
	v_max_f32_e32 v247, v247, v248
	v_mov_b32_e32 v248, v247
	s_nop 1
	v_permlane32_swap_b32_e32 v247, v248
	v_max3_f32 v247, v230, v247, v248
	v_cmp_neq_f32_e32 vcc, s33, v247
	s_nop 1
	v_cndmask_b32_e32 v248, 0, v247, vcc
	v_sub_f32_e32 v33, v230, v248
	v_mul_f32_e32 v33, 0x3e38aa3b, v33
	v_exp_f32_e32 v232, v33
	v_mul_f32_e32 v234, 0xbe38aa3b, v248
	v_mov_b32_e32 v230, v247
	s_add_u32 s8, s8, 1
	s_cmp_lt_u32 s8, s9
	s_cbranch_scc1 .Lat_loop_1
	s_branch .Lat_epilogue

.Lat_nors_l0:
	v_fmamk_f32 v34, v34, 0x3e38aa3b, v234
	v_fmamk_f32 v35, v35, 0x3e38aa3b, v234
	v_fmamk_f32 v36, v36, 0x3e38aa3b, v234
	ds_read_b64_tr_b16 v[168:169], v228 offset:3072
	s_waitcnt lgkmcnt(14)
	v_fmamk_f32 v37, v37, 0x3e38aa3b, v234
	v_fmamk_f32 v38, v38, 0x3e38aa3b, v234
	v_fmamk_f32 v39, v39, 0x3e38aa3b, v234
	ds_read_b64_tr_b16 v[170:171], v227 offset:4096
	s_waitcnt lgkmcnt(14)
	v_fmamk_f32 v40, v40, 0x3e38aa3b, v234
	v_fmamk_f32 v41, v41, 0x3e38aa3b, v234
	v_exp_f32_e32 v34, v34
	ds_read_b64_tr_b16 v[172:173], v227 offset:5120
	s_waitcnt lgkmcnt(14)
	v_exp_f32_e32 v35, v35
	v_exp_f32_e32 v36, v36
	v_exp_f32_e32 v37, v37
	ds_read_b64_tr_b16 v[174:175], v228 offset:4096
	s_waitcnt lgkmcnt(14)
	v_exp_f32_e32 v38, v38
	v_exp_f32_e32 v39, v39
	v_exp_f32_e32 v40, v40
	ds_read_b64_tr_b16 v[176:177], v228 offset:5120
	s_waitcnt lgkmcnt(14)
	v_exp_f32_e32 v41, v41
	v_add_f32_e32 v243, v34, v38
	v_add_f32_e32 v244, v35, v39
	ds_read_b64_tr_b16 v[178:179], v227 offset:6144
	s_waitcnt lgkmcnt(14)
	v_add_f32_e32 v245, v36, v40
	v_add_f32_e32 v246, v37, v41
	v_cvt_pk_bf16_f32 v34, v34, v35
	ds_read_b64_tr_b16 v[180:181], v227 offset:7168
	s_waitcnt lgkmcnt(14)
	v_cvt_pk_bf16_f32 v35, v36, v37
	v_cvt_pk_bf16_f32 v36, v38, v39
	v_cvt_pk_bf16_f32 v37, v40, v41
	ds_read_b64_tr_b16 v[182:183], v228 offset:6144
	s_waitcnt lgkmcnt(14)
	s_waitcnt lgkmcnt(13)
	v_mfma_f32_32x32x16_bf16 v[0:15], v[154:157], v[34:37], v[0:15]
	s_waitcnt lgkmcnt(11)
	v_mfma_f32_32x32x16_bf16 v[16:31], v[158:161], v[34:37], v[16:31]
	v_fmamk_f32 v42, v42, 0x3e38aa3b, v234
	v_fmamk_f32 v43, v43, 0x3e38aa3b, v234
	v_fmamk_f32 v44, v44, 0x3e38aa3b, v234
	ds_read_b64_tr_b16 v[184:185], v228 offset:7168
	v_fmamk_f32 v45, v45, 0x3e38aa3b, v234
	v_fmamk_f32 v46, v46, 0x3e38aa3b, v234
	v_fmamk_f32 v47, v47, 0x3e38aa3b, v234
	v_fmamk_f32 v48, v48, 0x3e38aa3b, v234
	v_fmamk_f32 v49, v49, 0x3e38aa3b, v234
	v_exp_f32_e32 v42, v42
	v_exp_f32_e32 v43, v43
	v_exp_f32_e32 v44, v44
	v_exp_f32_e32 v45, v45
	v_exp_f32_e32 v46, v46
	v_exp_f32_e32 v47, v47
	v_exp_f32_e32 v48, v48
	v_exp_f32_e32 v49, v49
	v_add_f32_e32 v243, v243, v42
	v_add_f32_e32 v244, v244, v43
	v_add_f32_e32 v245, v245, v44
	v_add_f32_e32 v246, v246, v45
	v_add_f32_e32 v243, v243, v46
	v_add_f32_e32 v244, v244, v47
	v_add_f32_e32 v245, v245, v48
	v_add_f32_e32 v246, v246, v49
	v_cvt_pk_bf16_f32 v42, v42, v43
	v_cvt_pk_bf16_f32 v43, v44, v45
	v_cvt_pk_bf16_f32 v44, v46, v47
	v_cvt_pk_bf16_f32 v45, v48, v49
	s_waitcnt lgkmcnt(10)
	v_mfma_f32_32x32x16_bf16 v[0:15], v[162:165], v[42:45], v[0:15]
	s_waitcnt lgkmcnt(8)
	v_mfma_f32_32x32x16_bf16 v[16:31], v[166:169], v[42:45], v[16:31]
	v_fmamk_f32 v50, v50, 0x3e38aa3b, v234
	v_fmamk_f32 v51, v51, 0x3e38aa3b, v234
	v_fmamk_f32 v52, v52, 0x3e38aa3b, v234
	v_fmamk_f32 v53, v53, 0x3e38aa3b, v234
	v_fmamk_f32 v54, v54, 0x3e38aa3b, v234
	v_fmamk_f32 v55, v55, 0x3e38aa3b, v234
	v_fmamk_f32 v56, v56, 0x3e38aa3b, v234
	v_fmamk_f32 v57, v57, 0x3e38aa3b, v234
	v_exp_f32_e32 v50, v50
	v_exp_f32_e32 v51, v51
	v_exp_f32_e32 v52, v52
	v_exp_f32_e32 v53, v53
	v_exp_f32_e32 v54, v54
	v_exp_f32_e32 v55, v55
	v_exp_f32_e32 v56, v56
	v_exp_f32_e32 v57, v57
	v_add_f32_e32 v243, v243, v50
	v_add_f32_e32 v244, v244, v51
	v_add_f32_e32 v245, v245, v52
	v_add_f32_e32 v246, v246, v53
	v_add_f32_e32 v243, v243, v54
	v_add_f32_e32 v244, v244, v55
	v_add_f32_e32 v245, v245, v56
	v_add_f32_e32 v246, v246, v57
	v_cvt_pk_bf16_f32 v50, v50, v51
	v_cvt_pk_bf16_f32 v51, v52, v53
	v_cvt_pk_bf16_f32 v52, v54, v55
	v_cvt_pk_bf16_f32 v53, v56, v57
	s_waitcnt lgkmcnt(6)
	v_mfma_f32_32x32x16_bf16 v[0:15], v[170:173], v[50:53], v[0:15]
	s_waitcnt lgkmcnt(4)
	v_mfma_f32_32x32x16_bf16 v[16:31], v[174:177], v[50:53], v[16:31]
	v_fmamk_f32 v58, v58, 0x3e38aa3b, v234
	v_fmamk_f32 v59, v59, 0x3e38aa3b, v234
	v_fmamk_f32 v60, v60, 0x3e38aa3b, v234
	v_fmamk_f32 v61, v61, 0x3e38aa3b, v234
	v_fmamk_f32 v62, v62, 0x3e38aa3b, v234
	v_fmamk_f32 v63, v63, 0x3e38aa3b, v234
	v_fmamk_f32 v64, v64, 0x3e38aa3b, v234
	v_fmamk_f32 v65, v65, 0x3e38aa3b, v234
	v_exp_f32_e32 v58, v58
	v_exp_f32_e32 v59, v59
	v_exp_f32_e32 v60, v60
	v_exp_f32_e32 v61, v61
	v_exp_f32_e32 v62, v62
	v_exp_f32_e32 v63, v63
	v_exp_f32_e32 v64, v64
	v_exp_f32_e32 v65, v65
	v_add_f32_e32 v243, v243, v58
	v_add_f32_e32 v244, v244, v59
	v_add_f32_e32 v245, v245, v60
	v_add_f32_e32 v246, v246, v61
	v_add_f32_e32 v243, v243, v62
	v_add_f32_e32 v244, v244, v63
	v_add_f32_e32 v245, v245, v64
	v_add_f32_e32 v246, v246, v65
	v_cvt_pk_bf16_f32 v58, v58, v59
	v_cvt_pk_bf16_f32 v59, v60, v61
	v_cvt_pk_bf16_f32 v60, v62, v63
	v_cvt_pk_bf16_f32 v61, v64, v65
	v_add_f32_e32 v243, v243, v244
	v_add_f32_e32 v245, v245, v246
	v_add_f32_e32 v243, v243, v245
	v_fma_f32 v231, v231, v232, v243
	s_waitcnt lgkmcnt(2)
	v_mfma_f32_32x32x16_bf16 v[0:15], v[178:181], v[58:61], v[0:15]
	s_waitcnt lgkmcnt(0)
	v_mfma_f32_32x32x16_bf16 v[16:31], v[182:185], v[58:61], v[16:31]
	s_add_u32 s8, s8, 1
	s_cmp_lt_u32 s8, s9
	s_cbranch_scc1 .Lat_loop_1
	s_branch .Lat_epilogue

.Lat_idle_1:
	s_waitcnt vmcnt(0)
	s_barrier
	s_add_u32 s8, s8, 1
	s_cmp_lt_u32 s8, s9
	s_cbranch_scc1 .Lat_loop_2
	s_branch .Lat_epilogue

.Lat_nors_f1:
	v_fmamk_f32 v70, v70, 0x3e38aa3b, v234
	v_fmamk_f32 v71, v71, 0x3e38aa3b, v234
	s_waitcnt lgkmcnt(7)
	v_mfma_f32_32x32x16_bf16 v[34:49], v[118:121], v[102:105], 0
	ds_read_b64_tr_b16 v[154:155], v227 offset:8192
	ds_read_b64_tr_b16 v[156:157], v227 offset:9216
	v_fmamk_f32 v72, v72, 0x3e38aa3b, v234
	v_fmamk_f32 v73, v73, 0x3e38aa3b, v234
	v_fmamk_f32 v74, v74, 0x3e38aa3b, v234
	v_fmamk_f32 v75, v75, 0x3e38aa3b, v234
	v_fmamk_f32 v76, v76, 0x3e38aa3b, v234
	v_fmamk_f32 v77, v77, 0x3e38aa3b, v234
	v_exp_f32_e32 v70, v70
	v_exp_f32_e32 v71, v71
	v_exp_f32_e32 v72, v72
	v_exp_f32_e32 v73, v73
	v_exp_f32_e32 v74, v74
	v_exp_f32_e32 v75, v75
	s_waitcnt lgkmcnt(8)
	v_mfma_f32_32x32x16_bf16 v[50:65], v[122:125], v[102:105], 0
	ds_read_b64_tr_b16 v[158:159], v228 offset:8192
	ds_read_b64_tr_b16 v[160:161], v228 offset:9216
	v_exp_f32_e32 v76, v76
	v_exp_f32_e32 v77, v77
	v_add_f32_e32 v243, v70, v74
	v_add_f32_e32 v244, v71, v75
	v_add_f32_e32 v245, v72, v76
	v_add_f32_e32 v246, v73, v77
	v_cvt_pk_bf16_f32 v70, v70, v71
	v_cvt_pk_bf16_f32 v71, v72, v73
	v_cvt_pk_bf16_f32 v72, v74, v75
	v_cvt_pk_bf16_f32 v73, v76, v77
	v_fmamk_f32 v78, v78, 0x3e38aa3b, v234
	v_fmamk_f32 v79, v79, 0x3e38aa3b, v234
	s_waitcnt lgkmcnt(9)
	v_mfma_f32_32x32x16_bf16 v[34:49], v[126:129], v[106:109], v[34:49]
	ds_read_b64_tr_b16 v[162:163], v227 offset:10240
	ds_read_b64_tr_b16 v[164:165], v227 offset:11264
	v_fmamk_f32 v80, v80, 0x3e38aa3b, v234
	v_fmamk_f32 v81, v81, 0x3e38aa3b, v234
	v_fmamk_f32 v82, v82, 0x3e38aa3b, v234
	v_fmamk_f32 v83, v83, 0x3e38aa3b, v234
	v_fmamk_f32 v84, v84, 0x3e38aa3b, v234
	v_fmamk_f32 v85, v85, 0x3e38aa3b, v234
	v_exp_f32_e32 v78, v78
	v_exp_f32_e32 v79, v79
	v_exp_f32_e32 v80, v80
	v_exp_f32_e32 v81, v81
	v_exp_f32_e32 v82, v82
	v_exp_f32_e32 v83, v83
	s_waitcnt lgkmcnt(10)
	v_mfma_f32_32x32x16_bf16 v[50:65], v[130:133], v[106:109], v[50:65]
	ds_read_b64_tr_b16 v[166:167], v228 offset:10240
	ds_read_b64_tr_b16 v[168:169], v228 offset:11264
	v_exp_f32_e32 v84, v84
	v_exp_f32_e32 v85, v85
	v_add_f32_e32 v243, v243, v78
	v_add_f32_e32 v244, v244, v79
	v_add_f32_e32 v245, v245, v80
	v_add_f32_e32 v246, v246, v81
	v_add_f32_e32 v243, v243, v82
	v_add_f32_e32 v244, v244, v83
	v_add_f32_e32 v245, v245, v84
	v_add_f32_e32 v246, v246, v85
	v_cvt_pk_bf16_f32 v78, v78, v79
	v_cvt_pk_bf16_f32 v79, v80, v81
	s_waitcnt lgkmcnt(11)
	v_mfma_f32_32x32x16_bf16 v[34:49], v[134:137], v[110:113], v[34:49]
	ds_read_b64_tr_b16 v[170:171], v227 offset:12288
	ds_read_b64_tr_b16 v[172:173], v227 offset:13312
	v_cvt_pk_bf16_f32 v80, v82, v83
	v_cvt_pk_bf16_f32 v81, v84, v85
	v_fmamk_f32 v86, v86, 0x3e38aa3b, v234
	v_fmamk_f32 v87, v87, 0x3e38aa3b, v234
	v_fmamk_f32 v88, v88, 0x3e38aa3b, v234
	v_fmamk_f32 v89, v89, 0x3e38aa3b, v234
	v_fmamk_f32 v90, v90, 0x3e38aa3b, v234
	v_fmamk_f32 v91, v91, 0x3e38aa3b, v234
	v_fmamk_f32 v92, v92, 0x3e38aa3b, v234
	v_fmamk_f32 v93, v93, 0x3e38aa3b, v234
	v_exp_f32_e32 v86, v86
	v_exp_f32_e32 v87, v87
	s_waitcnt lgkmcnt(12)
	v_mfma_f32_32x32x16_bf16 v[50:65], v[138:141], v[110:113], v[50:65]
	ds_read_b64_tr_b16 v[174:175], v228 offset:12288
	ds_read_b64_tr_b16 v[176:177], v228 offset:13312
	v_exp_f32_e32 v88, v88
	v_exp_f32_e32 v89, v89
	v_exp_f32_e32 v90, v90
	v_exp_f32_e32 v91, v91
	v_exp_f32_e32 v92, v92
	v_exp_f32_e32 v93, v93
	v_add_f32_e32 v243, v243, v86
	v_add_f32_e32 v244, v244, v87
	v_add_f32_e32 v245, v245, v88
	v_add_f32_e32 v246, v246, v89
	v_add_f32_e32 v243, v243, v90
	v_add_f32_e32 v244, v244, v91
	s_waitcnt lgkmcnt(13)
	v_mfma_f32_32x32x16_bf16 v[34:49], v[142:145], v[114:117], v[34:49]
	ds_read_b64_tr_b16 v[178:179], v227 offset:14336
	ds_read_b64_tr_b16 v[180:181], v227 offset:15360
	v_add_f32_e32 v245, v245, v92
	v_add_f32_e32 v246, v246, v93
	v_cvt_pk_bf16_f32 v86, v86, v87
	v_cvt_pk_bf16_f32 v87, v88, v89
	v_cvt_pk_bf16_f32 v88, v90, v91
	v_cvt_pk_bf16_f32 v89, v92, v93
	v_fmamk_f32 v94, v94, 0x3e38aa3b, v234
	v_fmamk_f32 v95, v95, 0x3e38aa3b, v234
	v_fmamk_f32 v96, v96, 0x3e38aa3b, v234
	v_fmamk_f32 v97, v97, 0x3e38aa3b, v234
	v_fmamk_f32 v98, v98, 0x3e38aa3b, v234
	v_fmamk_f32 v99, v99, 0x3e38aa3b, v234
	s_waitcnt lgkmcnt(14)
	v_mfma_f32_32x32x16_bf16 v[50:65], v[146:149], v[114:117], v[50:65]
	ds_read_b64_tr_b16 v[182:183], v228 offset:14336
	ds_read_b64_tr_b16 v[184:185], v228 offset:15360
	s_waitcnt lgkmcnt(14)
	v_fmamk_f32 v100, v100, 0x3e38aa3b, v234
	v_fmamk_f32 v101, v101, 0x3e38aa3b, v234
	v_exp_f32_e32 v94, v94
	v_exp_f32_e32 v95, v95
	v_exp_f32_e32 v96, v96
	v_exp_f32_e32 v97, v97
	v_exp_f32_e32 v98, v98
	v_exp_f32_e32 v99, v99
	v_exp_f32_e32 v100, v100
	v_exp_f32_e32 v101, v101
	v_add_f32_e32 v243, v243, v94
	v_add_f32_e32 v244, v244, v95
	v_add_f32_e32 v245, v245, v96
	v_add_f32_e32 v246, v246, v97
	s_waitcnt lgkmcnt(14)
	v_mfma_f32_32x32x16_bf16 v[0:15], v[154:157], v[70:73], v[0:15]
	ds_read_b128 v[118:121], v223 offset:24576
	v_add_f32_e32 v243, v243, v98
	v_add_f32_e32 v244, v244, v99
	v_add_f32_e32 v245, v245, v100
	v_add_f32_e32 v246, v246, v101
	v_cvt_pk_bf16_f32 v94, v94, v95
	v_cvt_pk_bf16_f32 v95, v96, v97
	v_cvt_pk_bf16_f32 v96, v98, v99
	v_cvt_pk_bf16_f32 v97, v100, v101
	v_add_f32_e32 v243, v243, v244
	v_add_f32_e32 v245, v245, v246
	v_add_f32_e32 v243, v243, v245
	v_fma_f32 v231, v231, v232, v243
	s_waitcnt lgkmcnt(13)
	v_mfma_f32_32x32x16_bf16 v[16:31], v[158:161], v[70:73], v[16:31]
	ds_read_b128 v[122:125], v223 offset:28672
	s_waitcnt vmcnt(4)
	v_lshrrev_b32_e32 v249, v229, v202
	v_lshrrev_b32_e32 v250, v229, v203
	v_bfe_i32 v235, v249, 0, 1
	v_bfe_i32 v236, v250, 0, 1
	v_bfe_i32 v237, v249, 1, 1
	v_bfe_i32 v238, v250, 1, 1
	v_bfe_i32 v239, v249, 2, 1
	v_bfe_i32 v240, v250, 2, 1
	v_bfe_i32 v241, v249, 3, 1
	v_bfe_i32 v242, v250, 3, 1
	v_bitop3_b32 v34, v34, s33, v235 bitop3:0xe4
	s_waitcnt lgkmcnt(12)
	v_mfma_f32_32x32x16_bf16 v[0:15], v[162:165], v[78:81], v[0:15]
	ds_read_b128 v[126:129], v224 offset:24576
	v_bitop3_b32 v50, v50, s33, v236 bitop3:0xe4
	v_bitop3_b32 v35, v35, s33, v237 bitop3:0xe4
	v_bitop3_b32 v51, v51, s33, v238 bitop3:0xe4
	v_bitop3_b32 v36, v36, s33, v239 bitop3:0xe4
	v_bitop3_b32 v52, v52, s33, v240 bitop3:0xe4
	v_bitop3_b32 v37, v37, s33, v241 bitop3:0xe4
	v_bitop3_b32 v53, v53, s33, v242 bitop3:0xe4
	v_max3_f32 v247, v34, s33, v50
	v_max3_f32 v248, v35, s33, v51
	v_max3_f32 v247, v247, v36, v52
	v_max3_f32 v248, v248, v37, v53
	v_bfe_i32 v235, v249, 8, 1
	s_waitcnt lgkmcnt(11)
	v_mfma_f32_32x32x16_bf16 v[16:31], v[166:169], v[78:81], v[16:31]
	ds_read_b128 v[130:133], v224 offset:28672
	v_bfe_i32 v236, v250, 8, 1
	v_bfe_i32 v237, v249, 9, 1
	v_bfe_i32 v238, v250, 9, 1
	v_bfe_i32 v239, v249, 10, 1
	v_bfe_i32 v240, v250, 10, 1
	v_bfe_i32 v241, v249, 11, 1
	v_bfe_i32 v242, v250, 11, 1
	v_bitop3_b32 v38, v38, s33, v235 bitop3:0xe4
	v_bitop3_b32 v54, v54, s33, v236 bitop3:0xe4
	v_bitop3_b32 v39, v39, s33, v237 bitop3:0xe4
	v_bitop3_b32 v55, v55, s33, v238 bitop3:0xe4
	v_bitop3_b32 v40, v40, s33, v239 bitop3:0xe4
	s_waitcnt lgkmcnt(10)
	v_mfma_f32_32x32x16_bf16 v[0:15], v[170:173], v[86:89], v[0:15]
	ds_read_b128 v[134:137], v225 offset:24576
	v_bitop3_b32 v56, v56, s33, v240 bitop3:0xe4
	v_bitop3_b32 v41, v41, s33, v241 bitop3:0xe4
	v_bitop3_b32 v57, v57, s33, v242 bitop3:0xe4
	v_max3_f32 v247, v247, v38, v54
	v_max3_f32 v248, v248, v39, v55
	v_max3_f32 v247, v247, v40, v56
	v_max3_f32 v248, v248, v41, v57
	v_bfe_i32 v235, v249, 16, 1
	v_bfe_i32 v236, v250, 16, 1
	v_bfe_i32 v237, v249, 17, 1
	v_bfe_i32 v238, v250, 17, 1
	v_bfe_i32 v239, v249, 18, 1
	s_waitcnt lgkmcnt(9)
	v_mfma_f32_32x32x16_bf16 v[16:31], v[174:177], v[86:89], v[16:31]
	ds_read_b128 v[138:141], v225 offset:28672
	v_bfe_i32 v240, v250, 18, 1
	v_bfe_i32 v241, v249, 19, 1
	v_bfe_i32 v242, v250, 19, 1
	v_bitop3_b32 v42, v42, s33, v235 bitop3:0xe4
	v_bitop3_b32 v58, v58, s33, v236 bitop3:0xe4
	v_bitop3_b32 v43, v43, s33, v237 bitop3:0xe4
	v_bitop3_b32 v59, v59, s33, v238 bitop3:0xe4
	v_bitop3_b32 v44, v44, s33, v239 bitop3:0xe4
	v_bitop3_b32 v60, v60, s33, v240 bitop3:0xe4
	v_bitop3_b32 v45, v45, s33, v241 bitop3:0xe4
	v_bitop3_b32 v61, v61, s33, v242 bitop3:0xe4
	v_max3_f32 v247, v247, v42, v58
	s_waitcnt lgkmcnt(8)
	v_mfma_f32_32x32x16_bf16 v[0:15], v[178:181], v[94:97], v[0:15]
	ds_read_b128 v[142:145], v226 offset:24576
	v_max3_f32 v248, v248, v43, v59
	v_max3_f32 v247, v247, v44, v60
	v_max3_f32 v248, v248, v45, v61
	v_bfe_i32 v235, v249, 24, 1
	v_bfe_i32 v236, v250, 24, 1
	v_bfe_i32 v237, v249, 25, 1
	v_bfe_i32 v238, v250, 25, 1
	v_bfe_i32 v239, v249, 26, 1
	v_bfe_i32 v240, v250, 26, 1
	v_bfe_i32 v241, v249, 27, 1
	v_bfe_i32 v242, v250, 27, 1
	v_bitop3_b32 v46, v46, s33, v235 bitop3:0xe4
	s_waitcnt lgkmcnt(7)
	v_mfma_f32_32x32x16_bf16 v[16:31], v[182:185], v[94:97], v[16:31]
	ds_read_b128 v[146:149], v226 offset:28672
	v_bitop3_b32 v62, v62, s33, v236 bitop3:0xe4
	v_bitop3_b32 v47, v47, s33, v237 bitop3:0xe4
	v_bitop3_b32 v63, v63, s33, v238 bitop3:0xe4
	v_bitop3_b32 v48, v48, s33, v239 bitop3:0xe4
	v_bitop3_b32 v64, v64, s33, v240 bitop3:0xe4
	v_bitop3_b32 v49, v49, s33, v241 bitop3:0xe4
	v_bitop3_b32 v65, v65, s33, v242 bitop3:0xe4
	v_max3_f32 v247, v247, v46, v62
	v_max3_f32 v248, v248, v47, v63
	v_max3_f32 v247, v247, v48, v64
	v_max3_f32 v248, v248, v49, v65
	v_max_f32_e32 v247, v247, v248
	v_mov_b32_e32 v248, v247
	s_nop 1
	v_permlane32_swap_b32_e32 v247, v248
	v_max3_f32 v247, v230, v247, v248
	v_cmp_neq_f32_e32 vcc, s33, v247
	s_nop 1
	v_cndmask_b32_e32 v248, 0, v247, vcc
	v_sub_f32_e32 v33, v230, v248
	v_mul_f32_e32 v33, 0x3e38aa3b, v33
	v_exp_f32_e32 v232, v33
	v_mul_f32_e32 v234, 0xbe38aa3b, v248
	v_mov_b32_e32 v230, v247
	s_waitcnt vmcnt(0)
	s_barrier
	s_add_u32 s8, s8, 1
	s_cmp_lt_u32 s8, s9
	s_cbranch_scc1 .Lat_loop_2
	s_branch .Lat_epilogue

.Lat_nors_l1:
	v_fmamk_f32 v70, v70, 0x3e38aa3b, v234
	v_fmamk_f32 v71, v71, 0x3e38aa3b, v234
	v_fmamk_f32 v72, v72, 0x3e38aa3b, v234
	ds_read_b64_tr_b16 v[168:169], v228 offset:11264
	s_waitcnt lgkmcnt(14)
	v_fmamk_f32 v73, v73, 0x3e38aa3b, v234
	v_fmamk_f32 v74, v74, 0x3e38aa3b, v234
	v_fmamk_f32 v75, v75, 0x3e38aa3b, v234
	ds_read_b64_tr_b16 v[170:171], v227 offset:12288
	s_waitcnt lgkmcnt(14)
	v_fmamk_f32 v76, v76, 0x3e38aa3b, v234
	v_fmamk_f32 v77, v77, 0x3e38aa3b, v234
	v_exp_f32_e32 v70, v70
	ds_read_b64_tr_b16 v[172:173], v227 offset:13312
	s_waitcnt lgkmcnt(14)
	v_exp_f32_e32 v71, v71
	v_exp_f32_e32 v72, v72
	v_exp_f32_e32 v73, v73
	ds_read_b64_tr_b16 v[174:175], v228 offset:12288
	s_waitcnt lgkmcnt(14)
	v_exp_f32_e32 v74, v74
	v_exp_f32_e32 v75, v75
	v_exp_f32_e32 v76, v76
	ds_read_b64_tr_b16 v[176:177], v228 offset:13312
	s_waitcnt lgkmcnt(14)
	v_exp_f32_e32 v77, v77
	v_add_f32_e32 v243, v70, v74
	v_add_f32_e32 v244, v71, v75
	ds_read_b64_tr_b16 v[178:179], v227 offset:14336
	s_waitcnt lgkmcnt(14)
	v_add_f32_e32 v245, v72, v76
	v_add_f32_e32 v246, v73, v77
	v_cvt_pk_bf16_f32 v70, v70, v71
	ds_read_b64_tr_b16 v[180:181], v227 offset:15360
	s_waitcnt lgkmcnt(14)
	v_cvt_pk_bf16_f32 v71, v72, v73
	v_cvt_pk_bf16_f32 v72, v74, v75
	v_cvt_pk_bf16_f32 v73, v76, v77
	ds_read_b64_tr_b16 v[182:183], v228 offset:14336
	s_waitcnt lgkmcnt(14)
	s_waitcnt lgkmcnt(13)
	v_mfma_f32_32x32x16_bf16 v[0:15], v[154:157], v[70:73], v[0:15]
	s_waitcnt lgkmcnt(11)
	v_mfma_f32_32x32x16_bf16 v[16:31], v[158:161], v[70:73], v[16:31]
	v_fmamk_f32 v78, v78, 0x3e38aa3b, v234
	v_fmamk_f32 v79, v79, 0x3e38aa3b, v234
	v_fmamk_f32 v80, v80, 0x3e38aa3b, v234
	ds_read_b64_tr_b16 v[184:185], v228 offset:15360
	v_fmamk_f32 v81, v81, 0x3e38aa3b, v234
	v_fmamk_f32 v82, v82, 0x3e38aa3b, v234
	v_fmamk_f32 v83, v83, 0x3e38aa3b, v234
	v_fmamk_f32 v84, v84, 0x3e38aa3b, v234
	v_fmamk_f32 v85, v85, 0x3e38aa3b, v234
	v_exp_f32_e32 v78, v78
	v_exp_f32_e32 v79, v79
	v_exp_f32_e32 v80, v80
	v_exp_f32_e32 v81, v81
	v_exp_f32_e32 v82, v82
	v_exp_f32_e32 v83, v83
	v_exp_f32_e32 v84, v84
	v_exp_f32_e32 v85, v85
	v_add_f32_e32 v243, v243, v78
	v_add_f32_e32 v244, v244, v79
	v_add_f32_e32 v245, v245, v80
	v_add_f32_e32 v246, v246, v81
	v_add_f32_e32 v243, v243, v82
	v_add_f32_e32 v244, v244, v83
	v_add_f32_e32 v245, v245, v84
	v_add_f32_e32 v246, v246, v85
	v_cvt_pk_bf16_f32 v78, v78, v79
	v_cvt_pk_bf16_f32 v79, v80, v81
	v_cvt_pk_bf16_f32 v80, v82, v83
	v_cvt_pk_bf16_f32 v81, v84, v85
	s_waitcnt lgkmcnt(10)
	v_mfma_f32_32x32x16_bf16 v[0:15], v[162:165], v[78:81], v[0:15]
	s_waitcnt lgkmcnt(8)
	v_mfma_f32_32x32x16_bf16 v[16:31], v[166:169], v[78:81], v[16:31]
	v_fmamk_f32 v86, v86, 0x3e38aa3b, v234
	v_fmamk_f32 v87, v87, 0x3e38aa3b, v234
	v_fmamk_f32 v88, v88, 0x3e38aa3b, v234
	v_fmamk_f32 v89, v89, 0x3e38aa3b, v234
	v_fmamk_f32 v90, v90, 0x3e38aa3b, v234
	v_fmamk_f32 v91, v91, 0x3e38aa3b, v234
	v_fmamk_f32 v92, v92, 0x3e38aa3b, v234
	v_fmamk_f32 v93, v93, 0x3e38aa3b, v234
	v_exp_f32_e32 v86, v86
	v_exp_f32_e32 v87, v87
	v_exp_f32_e32 v88, v88
	v_exp_f32_e32 v89, v89
	v_exp_f32_e32 v90, v90
	v_exp_f32_e32 v91, v91
	v_exp_f32_e32 v92, v92
	v_exp_f32_e32 v93, v93
	v_add_f32_e32 v243, v243, v86
	v_add_f32_e32 v244, v244, v87
	v_add_f32_e32 v245, v245, v88
	v_add_f32_e32 v246, v246, v89
	v_add_f32_e32 v243, v243, v90
	v_add_f32_e32 v244, v244, v91
	v_add_f32_e32 v245, v245, v92
	v_add_f32_e32 v246, v246, v93
	v_cvt_pk_bf16_f32 v86, v86, v87
	v_cvt_pk_bf16_f32 v87, v88, v89
	v_cvt_pk_bf16_f32 v88, v90, v91
	v_cvt_pk_bf16_f32 v89, v92, v93
	s_waitcnt lgkmcnt(6)
	v_mfma_f32_32x32x16_bf16 v[0:15], v[170:173], v[86:89], v[0:15]
	s_waitcnt lgkmcnt(4)
	v_mfma_f32_32x32x16_bf16 v[16:31], v[174:177], v[86:89], v[16:31]
	v_fmamk_f32 v94, v94, 0x3e38aa3b, v234
	v_fmamk_f32 v95, v95, 0x3e38aa3b, v234
	v_fmamk_f32 v96, v96, 0x3e38aa3b, v234
	v_fmamk_f32 v97, v97, 0x3e38aa3b, v234
	v_fmamk_f32 v98, v98, 0x3e38aa3b, v234
	v_fmamk_f32 v99, v99, 0x3e38aa3b, v234
	v_fmamk_f32 v100, v100, 0x3e38aa3b, v234
	v_fmamk_f32 v101, v101, 0x3e38aa3b, v234
	v_exp_f32_e32 v94, v94
	v_exp_f32_e32 v95, v95
	v_exp_f32_e32 v96, v96
	v_exp_f32_e32 v97, v97
	v_exp_f32_e32 v98, v98
	v_exp_f32_e32 v99, v99
	v_exp_f32_e32 v100, v100
	v_exp_f32_e32 v101, v101
	v_add_f32_e32 v243, v243, v94
	v_add_f32_e32 v244, v244, v95
	v_add_f32_e32 v245, v245, v96
	v_add_f32_e32 v246, v246, v97
	v_add_f32_e32 v243, v243, v98
	v_add_f32_e32 v244, v244, v99
	v_add_f32_e32 v245, v245, v100
	v_add_f32_e32 v246, v246, v101
	v_cvt_pk_bf16_f32 v94, v94, v95
	v_cvt_pk_bf16_f32 v95, v96, v97
	v_cvt_pk_bf16_f32 v96, v98, v99
	v_cvt_pk_bf16_f32 v97, v100, v101
	v_add_f32_e32 v243, v243, v244
	v_add_f32_e32 v245, v245, v246
	v_add_f32_e32 v243, v243, v245
	v_fma_f32 v231, v231, v232, v243
	s_waitcnt lgkmcnt(2)
	v_mfma_f32_32x32x16_bf16 v[0:15], v[178:181], v[94:97], v[0:15]
	s_waitcnt lgkmcnt(0)
	v_mfma_f32_32x32x16_bf16 v[16:31], v[182:185], v[94:97], v[16:31]
	s_waitcnt vmcnt(0)
	s_barrier
	s_add_u32 s8, s8, 1
	s_cmp_lt_u32 s8, s9
	s_cbranch_scc1 .Lat_loop_2
	s_branch .Lat_epilogue

.Lat_nors_f2:
	v_fmamk_f32 v34, v34, 0x3e38aa3b, v234
	v_fmamk_f32 v35, v35, 0x3e38aa3b, v234
	s_waitcnt lgkmcnt(7)
	v_mfma_f32_32x32x16_bf16 v[70:85], v[118:121], v[102:105], 0
	ds_read_b64_tr_b16 v[154:155], v227 offset:16384
	ds_read_b64_tr_b16 v[156:157], v227 offset:17408
	v_fmamk_f32 v36, v36, 0x3e38aa3b, v234
	v_fmamk_f32 v37, v37, 0x3e38aa3b, v234
	v_fmamk_f32 v38, v38, 0x3e38aa3b, v234
	v_fmamk_f32 v39, v39, 0x3e38aa3b, v234
	v_fmamk_f32 v40, v40, 0x3e38aa3b, v234
	v_fmamk_f32 v41, v41, 0x3e38aa3b, v234
	v_exp_f32_e32 v34, v34
	v_exp_f32_e32 v35, v35
	v_exp_f32_e32 v36, v36
	v_exp_f32_e32 v37, v37
	v_exp_f32_e32 v38, v38
	v_exp_f32_e32 v39, v39
	s_waitcnt lgkmcnt(8)
	v_mfma_f32_32x32x16_bf16 v[86:101], v[122:125], v[102:105], 0
	ds_read_b64_tr_b16 v[158:159], v228 offset:16384
	ds_read_b64_tr_b16 v[160:161], v228 offset:17408
	v_exp_f32_e32 v40, v40
	v_exp_f32_e32 v41, v41
	v_add_f32_e32 v243, v34, v38
	v_add_f32_e32 v244, v35, v39
	v_add_f32_e32 v245, v36, v40
	v_add_f32_e32 v246, v37, v41
	v_cvt_pk_bf16_f32 v34, v34, v35
	v_cvt_pk_bf16_f32 v35, v36, v37
	v_cvt_pk_bf16_f32 v36, v38, v39
	v_cvt_pk_bf16_f32 v37, v40, v41
	v_fmamk_f32 v42, v42, 0x3e38aa3b, v234
	v_fmamk_f32 v43, v43, 0x3e38aa3b, v234
	s_waitcnt lgkmcnt(9)
	v_mfma_f32_32x32x16_bf16 v[70:85], v[126:129], v[106:109], v[70:85]
	ds_read_b64_tr_b16 v[162:163], v227 offset:18432
	ds_read_b64_tr_b16 v[164:165], v227 offset:19456
	v_fmamk_f32 v44, v44, 0x3e38aa3b, v234
	v_fmamk_f32 v45, v45, 0x3e38aa3b, v234
	v_fmamk_f32 v46, v46, 0x3e38aa3b, v234
	v_fmamk_f32 v47, v47, 0x3e38aa3b, v234
	v_fmamk_f32 v48, v48, 0x3e38aa3b, v234
	v_fmamk_f32 v49, v49, 0x3e38aa3b, v234
	v_exp_f32_e32 v42, v42
	v_exp_f32_e32 v43, v43
	v_exp_f32_e32 v44, v44
	v_exp_f32_e32 v45, v45
	v_exp_f32_e32 v46, v46
	v_exp_f32_e32 v47, v47
	s_waitcnt lgkmcnt(10)
	v_mfma_f32_32x32x16_bf16 v[86:101], v[130:133], v[106:109], v[86:101]
	ds_read_b64_tr_b16 v[166:167], v228 offset:18432
	ds_read_b64_tr_b16 v[168:169], v228 offset:19456
	v_exp_f32_e32 v48, v48
	v_exp_f32_e32 v49, v49
	v_add_f32_e32 v243, v243, v42
	v_add_f32_e32 v244, v244, v43
	v_add_f32_e32 v245, v245, v44
	v_add_f32_e32 v246, v246, v45
	v_add_f32_e32 v243, v243, v46
	v_add_f32_e32 v244, v244, v47
	v_add_f32_e32 v245, v245, v48
	v_add_f32_e32 v246, v246, v49
	v_cvt_pk_bf16_f32 v42, v42, v43
	v_cvt_pk_bf16_f32 v43, v44, v45
	s_waitcnt lgkmcnt(11)
	v_mfma_f32_32x32x16_bf16 v[70:85], v[134:137], v[110:113], v[70:85]
	ds_read_b64_tr_b16 v[170:171], v227 offset:20480
	ds_read_b64_tr_b16 v[172:173], v227 offset:21504
	v_cvt_pk_bf16_f32 v44, v46, v47
	v_cvt_pk_bf16_f32 v45, v48, v49
	v_fmamk_f32 v50, v50, 0x3e38aa3b, v234
	v_fmamk_f32 v51, v51, 0x3e38aa3b, v234
	v_fmamk_f32 v52, v52, 0x3e38aa3b, v234
	v_fmamk_f32 v53, v53, 0x3e38aa3b, v234
	v_fmamk_f32 v54, v54, 0x3e38aa3b, v234
	v_fmamk_f32 v55, v55, 0x3e38aa3b, v234
	v_fmamk_f32 v56, v56, 0x3e38aa3b, v234
	v_fmamk_f32 v57, v57, 0x3e38aa3b, v234
	v_exp_f32_e32 v50, v50
	v_exp_f32_e32 v51, v51
	s_waitcnt lgkmcnt(12)
	v_mfma_f32_32x32x16_bf16 v[86:101], v[138:141], v[110:113], v[86:101]
	ds_read_b64_tr_b16 v[174:175], v228 offset:20480
	ds_read_b64_tr_b16 v[176:177], v228 offset:21504
	v_exp_f32_e32 v52, v52
	v_exp_f32_e32 v53, v53
	v_exp_f32_e32 v54, v54
	v_exp_f32_e32 v55, v55
	v_exp_f32_e32 v56, v56
	v_exp_f32_e32 v57, v57
	v_add_f32_e32 v243, v243, v50
	v_add_f32_e32 v244, v244, v51
	v_add_f32_e32 v245, v245, v52
	v_add_f32_e32 v246, v246, v53
	v_add_f32_e32 v243, v243, v54
	v_add_f32_e32 v244, v244, v55
	s_waitcnt lgkmcnt(13)
	v_mfma_f32_32x32x16_bf16 v[70:85], v[142:145], v[114:117], v[70:85]
	ds_read_b64_tr_b16 v[178:179], v227 offset:22528
	ds_read_b64_tr_b16 v[180:181], v227 offset:23552
	v_add_f32_e32 v245, v245, v56
	v_add_f32_e32 v246, v246, v57
	v_cvt_pk_bf16_f32 v50, v50, v51
	v_cvt_pk_bf16_f32 v51, v52, v53
	v_cvt_pk_bf16_f32 v52, v54, v55
	v_cvt_pk_bf16_f32 v53, v56, v57
	v_fmamk_f32 v58, v58, 0x3e38aa3b, v234
	v_fmamk_f32 v59, v59, 0x3e38aa3b, v234
	v_fmamk_f32 v60, v60, 0x3e38aa3b, v234
	v_fmamk_f32 v61, v61, 0x3e38aa3b, v234
	v_fmamk_f32 v62, v62, 0x3e38aa3b, v234
	v_fmamk_f32 v63, v63, 0x3e38aa3b, v234
	s_waitcnt lgkmcnt(14)
	v_mfma_f32_32x32x16_bf16 v[86:101], v[146:149], v[114:117], v[86:101]
	ds_read_b64_tr_b16 v[182:183], v228 offset:22528
	ds_read_b64_tr_b16 v[184:185], v228 offset:23552
	s_waitcnt lgkmcnt(14)
	v_fmamk_f32 v64, v64, 0x3e38aa3b, v234
	v_fmamk_f32 v65, v65, 0x3e38aa3b, v234
	v_exp_f32_e32 v58, v58
	v_exp_f32_e32 v59, v59
	v_exp_f32_e32 v60, v60
	v_exp_f32_e32 v61, v61
	v_exp_f32_e32 v62, v62
	v_exp_f32_e32 v63, v63
	v_exp_f32_e32 v64, v64
	v_exp_f32_e32 v65, v65
	v_add_f32_e32 v243, v243, v58
	v_add_f32_e32 v244, v244, v59
	v_add_f32_e32 v245, v245, v60
	v_add_f32_e32 v246, v246, v61
	s_waitcnt lgkmcnt(14)
	v_mfma_f32_32x32x16_bf16 v[0:15], v[154:157], v[34:37], v[0:15]
	ds_read_b128 v[118:121], v223 offset:0
	v_add_f32_e32 v243, v243, v62
	v_add_f32_e32 v244, v244, v63
	v_add_f32_e32 v245, v245, v64
	v_add_f32_e32 v246, v246, v65
	v_cvt_pk_bf16_f32 v58, v58, v59
	v_cvt_pk_bf16_f32 v59, v60, v61
	v_cvt_pk_bf16_f32 v60, v62, v63
	v_cvt_pk_bf16_f32 v61, v64, v65
	v_add_f32_e32 v243, v243, v244
	v_add_f32_e32 v245, v245, v246
	v_add_f32_e32 v243, v243, v245
	v_fma_f32 v231, v231, v232, v243
	s_waitcnt lgkmcnt(13)
	v_mfma_f32_32x32x16_bf16 v[16:31], v[158:161], v[34:37], v[16:31]
	ds_read_b128 v[122:125], v223 offset:4096
	v_lshrrev_b32_e32 v249, v229, v204
	v_lshrrev_b32_e32 v250, v229, v205
	v_bfe_i32 v235, v249, 0, 1
	v_bfe_i32 v236, v250, 0, 1
	v_bfe_i32 v237, v249, 1, 1
	v_bfe_i32 v238, v250, 1, 1
	v_bfe_i32 v239, v249, 2, 1
	v_bfe_i32 v240, v250, 2, 1
	v_bfe_i32 v241, v249, 3, 1
	v_bfe_i32 v242, v250, 3, 1
	v_bitop3_b32 v70, v70, s33, v235 bitop3:0xe4
	s_waitcnt lgkmcnt(12)
	v_mfma_f32_32x32x16_bf16 v[0:15], v[162:165], v[42:45], v[0:15]
	ds_read_b128 v[126:129], v224 offset:0
	v_bitop3_b32 v86, v86, s33, v236 bitop3:0xe4
	v_bitop3_b32 v71, v71, s33, v237 bitop3:0xe4
	v_bitop3_b32 v87, v87, s33, v238 bitop3:0xe4
	v_bitop3_b32 v72, v72, s33, v239 bitop3:0xe4
	v_bitop3_b32 v88, v88, s33, v240 bitop3:0xe4
	v_bitop3_b32 v73, v73, s33, v241 bitop3:0xe4
	v_bitop3_b32 v89, v89, s33, v242 bitop3:0xe4
	v_max3_f32 v247, v70, s33, v86
	v_max3_f32 v248, v71, s33, v87
	v_max3_f32 v247, v247, v72, v88
	v_max3_f32 v248, v248, v73, v89
	v_bfe_i32 v235, v249, 8, 1
	s_waitcnt lgkmcnt(11)
	v_mfma_f32_32x32x16_bf16 v[16:31], v[166:169], v[42:45], v[16:31]
	ds_read_b128 v[130:133], v224 offset:4096
	v_bfe_i32 v236, v250, 8, 1
	v_bfe_i32 v237, v249, 9, 1
	v_bfe_i32 v238, v250, 9, 1
	v_bfe_i32 v239, v249, 10, 1
	v_bfe_i32 v240, v250, 10, 1
	v_bfe_i32 v241, v249, 11, 1
	v_bfe_i32 v242, v250, 11, 1
	v_bitop3_b32 v74, v74, s33, v235 bitop3:0xe4
	v_bitop3_b32 v90, v90, s33, v236 bitop3:0xe4
	v_bitop3_b32 v75, v75, s33, v237 bitop3:0xe4
	v_bitop3_b32 v91, v91, s33, v238 bitop3:0xe4
	v_bitop3_b32 v76, v76, s33, v239 bitop3:0xe4
	s_waitcnt lgkmcnt(10)
	v_mfma_f32_32x32x16_bf16 v[0:15], v[170:173], v[50:53], v[0:15]
	ds_read_b128 v[134:137], v225 offset:0
	v_bitop3_b32 v92, v92, s33, v240 bitop3:0xe4
	v_bitop3_b32 v77, v77, s33, v241 bitop3:0xe4
	v_bitop3_b32 v93, v93, s33, v242 bitop3:0xe4
	v_max3_f32 v247, v247, v74, v90
	v_max3_f32 v248, v248, v75, v91
	v_max3_f32 v247, v247, v76, v92
	v_max3_f32 v248, v248, v77, v93
	v_bfe_i32 v235, v249, 16, 1
	v_bfe_i32 v236, v250, 16, 1
	v_bfe_i32 v237, v249, 17, 1
	v_bfe_i32 v238, v250, 17, 1
	v_bfe_i32 v239, v249, 18, 1
	s_waitcnt lgkmcnt(9)
	v_mfma_f32_32x32x16_bf16 v[16:31], v[174:177], v[50:53], v[16:31]
	ds_read_b128 v[138:141], v225 offset:4096
	v_bfe_i32 v240, v250, 18, 1
	v_bfe_i32 v241, v249, 19, 1
	v_bfe_i32 v242, v250, 19, 1
	v_bitop3_b32 v78, v78, s33, v235 bitop3:0xe4
	v_bitop3_b32 v94, v94, s33, v236 bitop3:0xe4
	v_bitop3_b32 v79, v79, s33, v237 bitop3:0xe4
	v_bitop3_b32 v95, v95, s33, v238 bitop3:0xe4
	v_bitop3_b32 v80, v80, s33, v239 bitop3:0xe4
	v_bitop3_b32 v96, v96, s33, v240 bitop3:0xe4
	v_bitop3_b32 v81, v81, s33, v241 bitop3:0xe4
	v_bitop3_b32 v97, v97, s33, v242 bitop3:0xe4
	v_max3_f32 v247, v247, v78, v94
	s_waitcnt lgkmcnt(8)
	v_mfma_f32_32x32x16_bf16 v[0:15], v[178:181], v[58:61], v[0:15]
	ds_read_b128 v[142:145], v226 offset:0
	v_max3_f32 v248, v248, v79, v95
	v_max3_f32 v247, v247, v80, v96
	v_max3_f32 v248, v248, v81, v97
	v_bfe_i32 v235, v249, 24, 1
	v_bfe_i32 v236, v250, 24, 1
	v_bfe_i32 v237, v249, 25, 1
	v_bfe_i32 v238, v250, 25, 1
	v_bfe_i32 v239, v249, 26, 1
	v_bfe_i32 v240, v250, 26, 1
	v_bfe_i32 v241, v249, 27, 1
	v_bfe_i32 v242, v250, 27, 1
	v_bitop3_b32 v82, v82, s33, v235 bitop3:0xe4
	s_waitcnt lgkmcnt(7)
	v_mfma_f32_32x32x16_bf16 v[16:31], v[182:185], v[58:61], v[16:31]
	ds_read_b128 v[146:149], v226 offset:4096
	v_bitop3_b32 v98, v98, s33, v236 bitop3:0xe4
	v_bitop3_b32 v83, v83, s33, v237 bitop3:0xe4
	v_bitop3_b32 v99, v99, s33, v238 bitop3:0xe4
	v_bitop3_b32 v84, v84, s33, v239 bitop3:0xe4
	v_bitop3_b32 v100, v100, s33, v240 bitop3:0xe4
	v_bitop3_b32 v85, v85, s33, v241 bitop3:0xe4
	v_bitop3_b32 v101, v101, s33, v242 bitop3:0xe4
	v_max3_f32 v247, v247, v82, v98
	v_max3_f32 v248, v248, v83, v99
	v_max3_f32 v247, v247, v84, v100
	v_max3_f32 v248, v248, v85, v101
	v_max_f32_e32 v247, v247, v248
	v_mov_b32_e32 v248, v247
	s_nop 1
	v_permlane32_swap_b32_e32 v247, v248
	v_max3_f32 v247, v230, v247, v248
	v_cmp_neq_f32_e32 vcc, s33, v247
	s_nop 1
	v_cndmask_b32_e32 v248, 0, v247, vcc
	v_sub_f32_e32 v33, v230, v248
	v_mul_f32_e32 v33, 0x3e38aa3b, v33
	v_exp_f32_e32 v232, v33
	v_mul_f32_e32 v234, 0xbe38aa3b, v248
	v_mov_b32_e32 v230, v247
	s_add_u32 s8, s8, 1
	s_cmp_lt_u32 s8, s9
	s_cbranch_scc1 .Lat_loop_3
	s_branch .Lat_epilogue

.Lat_nors_l2:
	v_fmamk_f32 v34, v34, 0x3e38aa3b, v234
	v_fmamk_f32 v35, v35, 0x3e38aa3b, v234
	v_fmamk_f32 v36, v36, 0x3e38aa3b, v234
	ds_read_b64_tr_b16 v[168:169], v228 offset:19456
	s_waitcnt lgkmcnt(14)
	v_fmamk_f32 v37, v37, 0x3e38aa3b, v234
	v_fmamk_f32 v38, v38, 0x3e38aa3b, v234
	v_fmamk_f32 v39, v39, 0x3e38aa3b, v234
	ds_read_b64_tr_b16 v[170:171], v227 offset:20480
	s_waitcnt lgkmcnt(14)
	v_fmamk_f32 v40, v40, 0x3e38aa3b, v234
	v_fmamk_f32 v41, v41, 0x3e38aa3b, v234
	v_exp_f32_e32 v34, v34
	ds_read_b64_tr_b16 v[172:173], v227 offset:21504
	s_waitcnt lgkmcnt(14)
	v_exp_f32_e32 v35, v35
	v_exp_f32_e32 v36, v36
	v_exp_f32_e32 v37, v37
	ds_read_b64_tr_b16 v[174:175], v228 offset:20480
	s_waitcnt lgkmcnt(14)
	v_exp_f32_e32 v38, v38
	v_exp_f32_e32 v39, v39
	v_exp_f32_e32 v40, v40
	ds_read_b64_tr_b16 v[176:177], v228 offset:21504
	s_waitcnt lgkmcnt(14)
	v_exp_f32_e32 v41, v41
	v_add_f32_e32 v243, v34, v38
	v_add_f32_e32 v244, v35, v39
	ds_read_b64_tr_b16 v[178:179], v227 offset:22528
	s_waitcnt lgkmcnt(14)
	v_add_f32_e32 v245, v36, v40
	v_add_f32_e32 v246, v37, v41
	v_cvt_pk_bf16_f32 v34, v34, v35
	ds_read_b64_tr_b16 v[180:181], v227 offset:23552
	s_waitcnt lgkmcnt(14)
	v_cvt_pk_bf16_f32 v35, v36, v37
	v_cvt_pk_bf16_f32 v36, v38, v39
	v_cvt_pk_bf16_f32 v37, v40, v41
	ds_read_b64_tr_b16 v[182:183], v228 offset:22528
	s_waitcnt lgkmcnt(14)
	s_waitcnt lgkmcnt(13)
	v_mfma_f32_32x32x16_bf16 v[0:15], v[154:157], v[34:37], v[0:15]
	s_waitcnt lgkmcnt(11)
	v_mfma_f32_32x32x16_bf16 v[16:31], v[158:161], v[34:37], v[16:31]
	v_fmamk_f32 v42, v42, 0x3e38aa3b, v234
	v_fmamk_f32 v43, v43, 0x3e38aa3b, v234
	v_fmamk_f32 v44, v44, 0x3e38aa3b, v234
	ds_read_b64_tr_b16 v[184:185], v228 offset:23552
	v_fmamk_f32 v45, v45, 0x3e38aa3b, v234
	v_fmamk_f32 v46, v46, 0x3e38aa3b, v234
	v_fmamk_f32 v47, v47, 0x3e38aa3b, v234
	v_fmamk_f32 v48, v48, 0x3e38aa3b, v234
	v_fmamk_f32 v49, v49, 0x3e38aa3b, v234
	v_exp_f32_e32 v42, v42
	v_exp_f32_e32 v43, v43
	v_exp_f32_e32 v44, v44
	v_exp_f32_e32 v45, v45
	v_exp_f32_e32 v46, v46
	v_exp_f32_e32 v47, v47
	v_exp_f32_e32 v48, v48
	v_exp_f32_e32 v49, v49
	v_add_f32_e32 v243, v243, v42
	v_add_f32_e32 v244, v244, v43
	v_add_f32_e32 v245, v245, v44
	v_add_f32_e32 v246, v246, v45
	v_add_f32_e32 v243, v243, v46
	v_add_f32_e32 v244, v244, v47
	v_add_f32_e32 v245, v245, v48
	v_add_f32_e32 v246, v246, v49
	v_cvt_pk_bf16_f32 v42, v42, v43
	v_cvt_pk_bf16_f32 v43, v44, v45
	v_cvt_pk_bf16_f32 v44, v46, v47
	v_cvt_pk_bf16_f32 v45, v48, v49
	s_waitcnt lgkmcnt(10)
	v_mfma_f32_32x32x16_bf16 v[0:15], v[162:165], v[42:45], v[0:15]
	s_waitcnt lgkmcnt(8)
	v_mfma_f32_32x32x16_bf16 v[16:31], v[166:169], v[42:45], v[16:31]
	v_fmamk_f32 v50, v50, 0x3e38aa3b, v234
	v_fmamk_f32 v51, v51, 0x3e38aa3b, v234
	v_fmamk_f32 v52, v52, 0x3e38aa3b, v234
	v_fmamk_f32 v53, v53, 0x3e38aa3b, v234
	v_fmamk_f32 v54, v54, 0x3e38aa3b, v234
	v_fmamk_f32 v55, v55, 0x3e38aa3b, v234
	v_fmamk_f32 v56, v56, 0x3e38aa3b, v234
	v_fmamk_f32 v57, v57, 0x3e38aa3b, v234
	v_exp_f32_e32 v50, v50
	v_exp_f32_e32 v51, v51
	v_exp_f32_e32 v52, v52
	v_exp_f32_e32 v53, v53
	v_exp_f32_e32 v54, v54
	v_exp_f32_e32 v55, v55
	v_exp_f32_e32 v56, v56
	v_exp_f32_e32 v57, v57
	v_add_f32_e32 v243, v243, v50
	v_add_f32_e32 v244, v244, v51
	v_add_f32_e32 v245, v245, v52
	v_add_f32_e32 v246, v246, v53
	v_add_f32_e32 v243, v243, v54
	v_add_f32_e32 v244, v244, v55
	v_add_f32_e32 v245, v245, v56
	v_add_f32_e32 v246, v246, v57
	v_cvt_pk_bf16_f32 v50, v50, v51
	v_cvt_pk_bf16_f32 v51, v52, v53
	v_cvt_pk_bf16_f32 v52, v54, v55
	v_cvt_pk_bf16_f32 v53, v56, v57
	s_waitcnt lgkmcnt(6)
	v_mfma_f32_32x32x16_bf16 v[0:15], v[170:173], v[50:53], v[0:15]
	s_waitcnt lgkmcnt(4)
	v_mfma_f32_32x32x16_bf16 v[16:31], v[174:177], v[50:53], v[16:31]
	v_fmamk_f32 v58, v58, 0x3e38aa3b, v234
	v_fmamk_f32 v59, v59, 0x3e38aa3b, v234
	v_fmamk_f32 v60, v60, 0x3e38aa3b, v234
	v_fmamk_f32 v61, v61, 0x3e38aa3b, v234
	v_fmamk_f32 v62, v62, 0x3e38aa3b, v234
	v_fmamk_f32 v63, v63, 0x3e38aa3b, v234
	v_fmamk_f32 v64, v64, 0x3e38aa3b, v234
	v_fmamk_f32 v65, v65, 0x3e38aa3b, v234
	v_exp_f32_e32 v58, v58
	v_exp_f32_e32 v59, v59
	v_exp_f32_e32 v60, v60
	v_exp_f32_e32 v61, v61
	v_exp_f32_e32 v62, v62
	v_exp_f32_e32 v63, v63
	v_exp_f32_e32 v64, v64
	v_exp_f32_e32 v65, v65
	v_add_f32_e32 v243, v243, v58
	v_add_f32_e32 v244, v244, v59
	v_add_f32_e32 v245, v245, v60
	v_add_f32_e32 v246, v246, v61
	v_add_f32_e32 v243, v243, v62
	v_add_f32_e32 v244, v244, v63
	v_add_f32_e32 v245, v245, v64
	v_add_f32_e32 v246, v246, v65
	v_cvt_pk_bf16_f32 v58, v58, v59
	v_cvt_pk_bf16_f32 v59, v60, v61
	v_cvt_pk_bf16_f32 v60, v62, v63
	v_cvt_pk_bf16_f32 v61, v64, v65
	v_add_f32_e32 v243, v243, v244
	v_add_f32_e32 v245, v245, v246
	v_add_f32_e32 v243, v243, v245
	v_fma_f32 v231, v231, v232, v243
	s_waitcnt lgkmcnt(2)
	v_mfma_f32_32x32x16_bf16 v[0:15], v[178:181], v[58:61], v[0:15]
	s_waitcnt lgkmcnt(0)
	v_mfma_f32_32x32x16_bf16 v[16:31], v[182:185], v[58:61], v[16:31]
	s_add_u32 s8, s8, 1
	s_cmp_lt_u32 s8, s9
	s_cbranch_scc1 .Lat_loop_3
	s_branch .Lat_epilogue

.Lat_nors_f3:
	v_fmamk_f32 v70, v70, 0x3e38aa3b, v234
	v_fmamk_f32 v71, v71, 0x3e38aa3b, v234
	s_waitcnt lgkmcnt(7)
	v_mfma_f32_32x32x16_bf16 v[34:49], v[118:121], v[102:105], 0
	ds_read_b64_tr_b16 v[154:155], v227 offset:24576
	ds_read_b64_tr_b16 v[156:157], v227 offset:25600
	v_fmamk_f32 v72, v72, 0x3e38aa3b, v234
	v_fmamk_f32 v73, v73, 0x3e38aa3b, v234
	v_fmamk_f32 v74, v74, 0x3e38aa3b, v234
	v_fmamk_f32 v75, v75, 0x3e38aa3b, v234
	v_fmamk_f32 v76, v76, 0x3e38aa3b, v234
	v_fmamk_f32 v77, v77, 0x3e38aa3b, v234
	v_exp_f32_e32 v70, v70
	v_exp_f32_e32 v71, v71
	v_exp_f32_e32 v72, v72
	v_exp_f32_e32 v73, v73
	v_exp_f32_e32 v74, v74
	v_exp_f32_e32 v75, v75
	s_waitcnt lgkmcnt(8)
	v_mfma_f32_32x32x16_bf16 v[50:65], v[122:125], v[102:105], 0
	ds_read_b64_tr_b16 v[158:159], v228 offset:24576
	ds_read_b64_tr_b16 v[160:161], v228 offset:25600
	v_exp_f32_e32 v76, v76
	v_exp_f32_e32 v77, v77
	v_add_f32_e32 v243, v70, v74
	v_add_f32_e32 v244, v71, v75
	v_add_f32_e32 v245, v72, v76
	v_add_f32_e32 v246, v73, v77
	v_cvt_pk_bf16_f32 v70, v70, v71
	v_cvt_pk_bf16_f32 v71, v72, v73
	v_cvt_pk_bf16_f32 v72, v74, v75
	v_cvt_pk_bf16_f32 v73, v76, v77
	v_fmamk_f32 v78, v78, 0x3e38aa3b, v234
	v_fmamk_f32 v79, v79, 0x3e38aa3b, v234
	s_waitcnt lgkmcnt(9)
	v_mfma_f32_32x32x16_bf16 v[34:49], v[126:129], v[106:109], v[34:49]
	ds_read_b64_tr_b16 v[162:163], v227 offset:26624
	ds_read_b64_tr_b16 v[164:165], v227 offset:27648
	v_fmamk_f32 v80, v80, 0x3e38aa3b, v234
	v_fmamk_f32 v81, v81, 0x3e38aa3b, v234
	v_fmamk_f32 v82, v82, 0x3e38aa3b, v234
	v_fmamk_f32 v83, v83, 0x3e38aa3b, v234
	v_fmamk_f32 v84, v84, 0x3e38aa3b, v234
	v_fmamk_f32 v85, v85, 0x3e38aa3b, v234
	v_exp_f32_e32 v78, v78
	v_exp_f32_e32 v79, v79
	v_exp_f32_e32 v80, v80
	v_exp_f32_e32 v81, v81
	v_exp_f32_e32 v82, v82
	v_exp_f32_e32 v83, v83
	s_waitcnt lgkmcnt(10)
	v_mfma_f32_32x32x16_bf16 v[50:65], v[130:133], v[106:109], v[50:65]
	ds_read_b64_tr_b16 v[166:167], v228 offset:26624
	ds_read_b64_tr_b16 v[168:169], v228 offset:27648
	v_exp_f32_e32 v84, v84
	v_exp_f32_e32 v85, v85
	v_add_f32_e32 v243, v243, v78
	v_add_f32_e32 v244, v244, v79
	v_add_f32_e32 v245, v245, v80
	v_add_f32_e32 v246, v246, v81
	v_add_f32_e32 v243, v243, v82
	v_add_f32_e32 v244, v244, v83
	v_add_f32_e32 v245, v245, v84
	v_add_f32_e32 v246, v246, v85
	v_cvt_pk_bf16_f32 v78, v78, v79
	v_cvt_pk_bf16_f32 v79, v80, v81
	s_waitcnt lgkmcnt(11)
	v_mfma_f32_32x32x16_bf16 v[34:49], v[134:137], v[110:113], v[34:49]
	ds_read_b64_tr_b16 v[170:171], v227 offset:28672
	ds_read_b64_tr_b16 v[172:173], v227 offset:29696
	v_cvt_pk_bf16_f32 v80, v82, v83
	v_cvt_pk_bf16_f32 v81, v84, v85
	v_fmamk_f32 v86, v86, 0x3e38aa3b, v234
	v_fmamk_f32 v87, v87, 0x3e38aa3b, v234
	v_fmamk_f32 v88, v88, 0x3e38aa3b, v234
	v_fmamk_f32 v89, v89, 0x3e38aa3b, v234
	v_fmamk_f32 v90, v90, 0x3e38aa3b, v234
	v_fmamk_f32 v91, v91, 0x3e38aa3b, v234
	v_fmamk_f32 v92, v92, 0x3e38aa3b, v234
	v_fmamk_f32 v93, v93, 0x3e38aa3b, v234
	v_exp_f32_e32 v86, v86
	v_exp_f32_e32 v87, v87
	s_waitcnt lgkmcnt(12)
	v_mfma_f32_32x32x16_bf16 v[50:65], v[138:141], v[110:113], v[50:65]
	ds_read_b64_tr_b16 v[174:175], v228 offset:28672
	ds_read_b64_tr_b16 v[176:177], v228 offset:29696
	v_exp_f32_e32 v88, v88
	v_exp_f32_e32 v89, v89
	v_exp_f32_e32 v90, v90
	v_exp_f32_e32 v91, v91
	v_exp_f32_e32 v92, v92
	v_exp_f32_e32 v93, v93
	v_add_f32_e32 v243, v243, v86
	v_add_f32_e32 v244, v244, v87
	v_add_f32_e32 v245, v245, v88
	v_add_f32_e32 v246, v246, v89
	v_add_f32_e32 v243, v243, v90
	v_add_f32_e32 v244, v244, v91
	s_waitcnt lgkmcnt(13)
	v_mfma_f32_32x32x16_bf16 v[34:49], v[142:145], v[114:117], v[34:49]
	ds_read_b64_tr_b16 v[178:179], v227 offset:30720
	ds_read_b64_tr_b16 v[180:181], v227 offset:31744
	v_add_f32_e32 v245, v245, v92
	v_add_f32_e32 v246, v246, v93
	v_cvt_pk_bf16_f32 v86, v86, v87
	v_cvt_pk_bf16_f32 v87, v88, v89
	v_cvt_pk_bf16_f32 v88, v90, v91
	v_cvt_pk_bf16_f32 v89, v92, v93
	v_fmamk_f32 v94, v94, 0x3e38aa3b, v234
	v_fmamk_f32 v95, v95, 0x3e38aa3b, v234
	v_fmamk_f32 v96, v96, 0x3e38aa3b, v234
	v_fmamk_f32 v97, v97, 0x3e38aa3b, v234
	v_fmamk_f32 v98, v98, 0x3e38aa3b, v234
	v_fmamk_f32 v99, v99, 0x3e38aa3b, v234
	s_waitcnt lgkmcnt(14)
	v_mfma_f32_32x32x16_bf16 v[50:65], v[146:149], v[114:117], v[50:65]
	ds_read_b64_tr_b16 v[182:183], v228 offset:30720
	ds_read_b64_tr_b16 v[184:185], v228 offset:31744
	s_waitcnt lgkmcnt(14)
	v_fmamk_f32 v100, v100, 0x3e38aa3b, v234
	v_fmamk_f32 v101, v101, 0x3e38aa3b, v234
	v_exp_f32_e32 v94, v94
	v_exp_f32_e32 v95, v95
	v_exp_f32_e32 v96, v96
	v_exp_f32_e32 v97, v97
	v_exp_f32_e32 v98, v98
	v_exp_f32_e32 v99, v99
	v_exp_f32_e32 v100, v100
	v_exp_f32_e32 v101, v101
	v_add_f32_e32 v243, v243, v94
	v_add_f32_e32 v244, v244, v95
	v_add_f32_e32 v245, v245, v96
	v_add_f32_e32 v246, v246, v97
	s_waitcnt lgkmcnt(14)
	v_mfma_f32_32x32x16_bf16 v[0:15], v[154:157], v[70:73], v[0:15]
	ds_read_b128 v[118:121], v223 offset:8192
	v_add_f32_e32 v243, v243, v98
	v_add_f32_e32 v244, v244, v99
	v_add_f32_e32 v245, v245, v100
	v_add_f32_e32 v246, v246, v101
	v_cvt_pk_bf16_f32 v94, v94, v95
	v_cvt_pk_bf16_f32 v95, v96, v97
	v_cvt_pk_bf16_f32 v96, v98, v99
	v_cvt_pk_bf16_f32 v97, v100, v101
	v_add_f32_e32 v243, v243, v244
	v_add_f32_e32 v245, v245, v246
	v_add_f32_e32 v243, v243, v245
	v_fma_f32 v231, v231, v232, v243
	s_waitcnt lgkmcnt(13)
	v_mfma_f32_32x32x16_bf16 v[16:31], v[158:161], v[70:73], v[16:31]
	ds_read_b128 v[122:125], v223 offset:12288
	s_waitcnt vmcnt(4)
	v_lshrrev_b32_e32 v249, v229, v198
	v_lshrrev_b32_e32 v250, v229, v199
	v_bfe_i32 v235, v249, 0, 1
	v_bfe_i32 v236, v250, 0, 1
	v_bfe_i32 v237, v249, 1, 1
	v_bfe_i32 v238, v250, 1, 1
	v_bfe_i32 v239, v249, 2, 1
	v_bfe_i32 v240, v250, 2, 1
	v_bfe_i32 v241, v249, 3, 1
	v_bfe_i32 v242, v250, 3, 1
	v_bitop3_b32 v34, v34, s33, v235 bitop3:0xe4
	s_waitcnt lgkmcnt(12)
	v_mfma_f32_32x32x16_bf16 v[0:15], v[162:165], v[78:81], v[0:15]
	ds_read_b128 v[126:129], v224 offset:8192
	v_bitop3_b32 v50, v50, s33, v236 bitop3:0xe4
	v_bitop3_b32 v35, v35, s33, v237 bitop3:0xe4
	v_bitop3_b32 v51, v51, s33, v238 bitop3:0xe4
	v_bitop3_b32 v36, v36, s33, v239 bitop3:0xe4
	v_bitop3_b32 v52, v52, s33, v240 bitop3:0xe4
	v_bitop3_b32 v37, v37, s33, v241 bitop3:0xe4
	v_bitop3_b32 v53, v53, s33, v242 bitop3:0xe4
	v_max3_f32 v247, v34, s33, v50
	v_max3_f32 v248, v35, s33, v51
	v_max3_f32 v247, v247, v36, v52
	v_max3_f32 v248, v248, v37, v53
	v_bfe_i32 v235, v249, 8, 1
	s_waitcnt lgkmcnt(11)
	v_mfma_f32_32x32x16_bf16 v[16:31], v[166:169], v[78:81], v[16:31]
	ds_read_b128 v[130:133], v224 offset:12288
	v_bfe_i32 v236, v250, 8, 1
	v_bfe_i32 v237, v249, 9, 1
	v_bfe_i32 v238, v250, 9, 1
	v_bfe_i32 v239, v249, 10, 1
	v_bfe_i32 v240, v250, 10, 1
	v_bfe_i32 v241, v249, 11, 1
	v_bfe_i32 v242, v250, 11, 1
	v_bitop3_b32 v38, v38, s33, v235 bitop3:0xe4
	v_bitop3_b32 v54, v54, s33, v236 bitop3:0xe4
	v_bitop3_b32 v39, v39, s33, v237 bitop3:0xe4
	v_bitop3_b32 v55, v55, s33, v238 bitop3:0xe4
	v_bitop3_b32 v40, v40, s33, v239 bitop3:0xe4
	s_waitcnt lgkmcnt(10)
	v_mfma_f32_32x32x16_bf16 v[0:15], v[170:173], v[86:89], v[0:15]
	ds_read_b128 v[134:137], v225 offset:8192
	v_bitop3_b32 v56, v56, s33, v240 bitop3:0xe4
	v_bitop3_b32 v41, v41, s33, v241 bitop3:0xe4
	v_bitop3_b32 v57, v57, s33, v242 bitop3:0xe4
	v_max3_f32 v247, v247, v38, v54
	v_max3_f32 v248, v248, v39, v55
	v_max3_f32 v247, v247, v40, v56
	v_max3_f32 v248, v248, v41, v57
	v_bfe_i32 v235, v249, 16, 1
	v_bfe_i32 v236, v250, 16, 1
	v_bfe_i32 v237, v249, 17, 1
	v_bfe_i32 v238, v250, 17, 1
	v_bfe_i32 v239, v249, 18, 1
	s_waitcnt lgkmcnt(9)
	v_mfma_f32_32x32x16_bf16 v[16:31], v[174:177], v[86:89], v[16:31]
	ds_read_b128 v[138:141], v225 offset:12288
	v_bfe_i32 v240, v250, 18, 1
	v_bfe_i32 v241, v249, 19, 1
	v_bfe_i32 v242, v250, 19, 1
	v_bitop3_b32 v42, v42, s33, v235 bitop3:0xe4
	v_bitop3_b32 v58, v58, s33, v236 bitop3:0xe4
	v_bitop3_b32 v43, v43, s33, v237 bitop3:0xe4
	v_bitop3_b32 v59, v59, s33, v238 bitop3:0xe4
	v_bitop3_b32 v44, v44, s33, v239 bitop3:0xe4
	v_bitop3_b32 v60, v60, s33, v240 bitop3:0xe4
	v_bitop3_b32 v45, v45, s33, v241 bitop3:0xe4
	v_bitop3_b32 v61, v61, s33, v242 bitop3:0xe4
	v_max3_f32 v247, v247, v42, v58
	s_waitcnt lgkmcnt(8)
	v_mfma_f32_32x32x16_bf16 v[0:15], v[178:181], v[94:97], v[0:15]
	ds_read_b128 v[142:145], v226 offset:8192
	v_max3_f32 v248, v248, v43, v59
	v_max3_f32 v247, v247, v44, v60
	v_max3_f32 v248, v248, v45, v61
	v_bfe_i32 v235, v249, 24, 1
	v_bfe_i32 v236, v250, 24, 1
	v_bfe_i32 v237, v249, 25, 1
	v_bfe_i32 v238, v250, 25, 1
	v_bfe_i32 v239, v249, 26, 1
	v_bfe_i32 v240, v250, 26, 1
	v_bfe_i32 v241, v249, 27, 1
	v_bfe_i32 v242, v250, 27, 1
	v_bitop3_b32 v46, v46, s33, v235 bitop3:0xe4
	s_waitcnt lgkmcnt(7)
	v_mfma_f32_32x32x16_bf16 v[16:31], v[182:185], v[94:97], v[16:31]
	ds_read_b128 v[146:149], v226 offset:12288
	v_bitop3_b32 v62, v62, s33, v236 bitop3:0xe4
	v_bitop3_b32 v47, v47, s33, v237 bitop3:0xe4
	v_bitop3_b32 v63, v63, s33, v238 bitop3:0xe4
	v_bitop3_b32 v48, v48, s33, v239 bitop3:0xe4
	v_bitop3_b32 v64, v64, s33, v240 bitop3:0xe4
	v_bitop3_b32 v49, v49, s33, v241 bitop3:0xe4
	v_bitop3_b32 v65, v65, s33, v242 bitop3:0xe4
	v_max3_f32 v247, v247, v46, v62
	v_max3_f32 v248, v248, v47, v63
	v_max3_f32 v247, v247, v48, v64
	v_max3_f32 v248, v248, v49, v65
	v_max_f32_e32 v247, v247, v248
	v_mov_b32_e32 v248, v247
	s_nop 1
	v_permlane32_swap_b32_e32 v247, v248
	v_max3_f32 v247, v230, v247, v248
	v_cmp_neq_f32_e32 vcc, s33, v247
	s_nop 1
	v_cndmask_b32_e32 v248, 0, v247, vcc
	v_sub_f32_e32 v33, v230, v248
	v_mul_f32_e32 v33, 0x3e38aa3b, v33
	v_exp_f32_e32 v232, v33
	v_mul_f32_e32 v234, 0xbe38aa3b, v248
	v_mov_b32_e32 v230, v247
	s_waitcnt vmcnt(0)
	s_barrier
	s_add_u32 s8, s8, 1
	s_cmp_lt_u32 s8, s9
	s_cbranch_scc1 .Lat_loop_0
	s_branch .Lat_epilogue

.Lat_nors_l3:
	v_fmamk_f32 v70, v70, 0x3e38aa3b, v234
	v_fmamk_f32 v71, v71, 0x3e38aa3b, v234
	v_fmamk_f32 v72, v72, 0x3e38aa3b, v234
	ds_read_b64_tr_b16 v[168:169], v228 offset:27648
	s_waitcnt lgkmcnt(14)
	v_fmamk_f32 v73, v73, 0x3e38aa3b, v234
	v_fmamk_f32 v74, v74, 0x3e38aa3b, v234
	v_fmamk_f32 v75, v75, 0x3e38aa3b, v234
	ds_read_b64_tr_b16 v[170:171], v227 offset:28672
	s_waitcnt lgkmcnt(14)
	v_fmamk_f32 v76, v76, 0x3e38aa3b, v234
	v_fmamk_f32 v77, v77, 0x3e38aa3b, v234
	v_exp_f32_e32 v70, v70
	ds_read_b64_tr_b16 v[172:173], v227 offset:29696
	s_waitcnt lgkmcnt(14)
	v_exp_f32_e32 v71, v71
	v_exp_f32_e32 v72, v72
	v_exp_f32_e32 v73, v73
	ds_read_b64_tr_b16 v[174:175], v228 offset:28672
	s_waitcnt lgkmcnt(14)
	v_exp_f32_e32 v74, v74
	v_exp_f32_e32 v75, v75
	v_exp_f32_e32 v76, v76
	ds_read_b64_tr_b16 v[176:177], v228 offset:29696
	s_waitcnt lgkmcnt(14)
	v_exp_f32_e32 v77, v77
	v_add_f32_e32 v243, v70, v74
	v_add_f32_e32 v244, v71, v75
	ds_read_b64_tr_b16 v[178:179], v227 offset:30720
	s_waitcnt lgkmcnt(14)
	v_add_f32_e32 v245, v72, v76
	v_add_f32_e32 v246, v73, v77
	v_cvt_pk_bf16_f32 v70, v70, v71
	ds_read_b64_tr_b16 v[180:181], v227 offset:31744
	s_waitcnt lgkmcnt(14)
	v_cvt_pk_bf16_f32 v71, v72, v73
	v_cvt_pk_bf16_f32 v72, v74, v75
	v_cvt_pk_bf16_f32 v73, v76, v77
	ds_read_b64_tr_b16 v[182:183], v228 offset:30720
	s_waitcnt lgkmcnt(14)
	s_waitcnt lgkmcnt(13)
	v_mfma_f32_32x32x16_bf16 v[0:15], v[154:157], v[70:73], v[0:15]
	s_waitcnt lgkmcnt(11)
	v_mfma_f32_32x32x16_bf16 v[16:31], v[158:161], v[70:73], v[16:31]
	v_fmamk_f32 v78, v78, 0x3e38aa3b, v234
	v_fmamk_f32 v79, v79, 0x3e38aa3b, v234
	v_fmamk_f32 v80, v80, 0x3e38aa3b, v234
	ds_read_b64_tr_b16 v[184:185], v228 offset:31744
	v_fmamk_f32 v81, v81, 0x3e38aa3b, v234
	v_fmamk_f32 v82, v82, 0x3e38aa3b, v234
	v_fmamk_f32 v83, v83, 0x3e38aa3b, v234
	v_fmamk_f32 v84, v84, 0x3e38aa3b, v234
	v_fmamk_f32 v85, v85, 0x3e38aa3b, v234
	v_exp_f32_e32 v78, v78
	v_exp_f32_e32 v79, v79
	v_exp_f32_e32 v80, v80
	v_exp_f32_e32 v81, v81
	v_exp_f32_e32 v82, v82
	v_exp_f32_e32 v83, v83
	v_exp_f32_e32 v84, v84
	v_exp_f32_e32 v85, v85
	v_add_f32_e32 v243, v243, v78
	v_add_f32_e32 v244, v244, v79
	v_add_f32_e32 v245, v245, v80
	v_add_f32_e32 v246, v246, v81
	v_add_f32_e32 v243, v243, v82
	v_add_f32_e32 v244, v244, v83
	v_add_f32_e32 v245, v245, v84
	v_add_f32_e32 v246, v246, v85
	v_cvt_pk_bf16_f32 v78, v78, v79
	v_cvt_pk_bf16_f32 v79, v80, v81
	v_cvt_pk_bf16_f32 v80, v82, v83
	v_cvt_pk_bf16_f32 v81, v84, v85
	s_waitcnt lgkmcnt(10)
	v_mfma_f32_32x32x16_bf16 v[0:15], v[162:165], v[78:81], v[0:15]
	s_waitcnt lgkmcnt(8)
	v_mfma_f32_32x32x16_bf16 v[16:31], v[166:169], v[78:81], v[16:31]
	v_fmamk_f32 v86, v86, 0x3e38aa3b, v234
	v_fmamk_f32 v87, v87, 0x3e38aa3b, v234
	v_fmamk_f32 v88, v88, 0x3e38aa3b, v234
	v_fmamk_f32 v89, v89, 0x3e38aa3b, v234
	v_fmamk_f32 v90, v90, 0x3e38aa3b, v234
	v_fmamk_f32 v91, v91, 0x3e38aa3b, v234
	v_fmamk_f32 v92, v92, 0x3e38aa3b, v234
	v_fmamk_f32 v93, v93, 0x3e38aa3b, v234
	v_exp_f32_e32 v86, v86
	v_exp_f32_e32 v87, v87
	v_exp_f32_e32 v88, v88
	v_exp_f32_e32 v89, v89
	v_exp_f32_e32 v90, v90
	v_exp_f32_e32 v91, v91
	v_exp_f32_e32 v92, v92
	v_exp_f32_e32 v93, v93
	v_add_f32_e32 v243, v243, v86
	v_add_f32_e32 v244, v244, v87
	v_add_f32_e32 v245, v245, v88
	v_add_f32_e32 v246, v246, v89
	v_add_f32_e32 v243, v243, v90
	v_add_f32_e32 v244, v244, v91
	v_add_f32_e32 v245, v245, v92
	v_add_f32_e32 v246, v246, v93
	v_cvt_pk_bf16_f32 v86, v86, v87
	v_cvt_pk_bf16_f32 v87, v88, v89
	v_cvt_pk_bf16_f32 v88, v90, v91
	v_cvt_pk_bf16_f32 v89, v92, v93
	s_waitcnt lgkmcnt(6)
	v_mfma_f32_32x32x16_bf16 v[0:15], v[170:173], v[86:89], v[0:15]
	s_waitcnt lgkmcnt(4)
	v_mfma_f32_32x32x16_bf16 v[16:31], v[174:177], v[86:89], v[16:31]
	v_fmamk_f32 v94, v94, 0x3e38aa3b, v234
	v_fmamk_f32 v95, v95, 0x3e38aa3b, v234
	v_fmamk_f32 v96, v96, 0x3e38aa3b, v234
	v_fmamk_f32 v97, v97, 0x3e38aa3b, v234
	v_fmamk_f32 v98, v98, 0x3e38aa3b, v234
	v_fmamk_f32 v99, v99, 0x3e38aa3b, v234
	v_fmamk_f32 v100, v100, 0x3e38aa3b, v234
	v_fmamk_f32 v101, v101, 0x3e38aa3b, v234
	v_exp_f32_e32 v94, v94
	v_exp_f32_e32 v95, v95
	v_exp_f32_e32 v96, v96
	v_exp_f32_e32 v97, v97
	v_exp_f32_e32 v98, v98
	v_exp_f32_e32 v99, v99
	v_exp_f32_e32 v100, v100
	v_exp_f32_e32 v101, v101
	v_add_f32_e32 v243, v243, v94
	v_add_f32_e32 v244, v244, v95
	v_add_f32_e32 v245, v245, v96
	v_add_f32_e32 v246, v246, v97
	v_add_f32_e32 v243, v243, v98
	v_add_f32_e32 v244, v244, v99
	v_add_f32_e32 v245, v245, v100
	v_add_f32_e32 v246, v246, v101
	v_cvt_pk_bf16_f32 v94, v94, v95
	v_cvt_pk_bf16_f32 v95, v96, v97
	v_cvt_pk_bf16_f32 v96, v98, v99
	v_cvt_pk_bf16_f32 v97, v100, v101
	v_add_f32_e32 v243, v243, v244
	v_add_f32_e32 v245, v245, v246
	v_add_f32_e32 v243, v243, v245
	v_fma_f32 v231, v231, v232, v243
	s_waitcnt lgkmcnt(2)
	v_mfma_f32_32x32x16_bf16 v[0:15], v[178:181], v[94:97], v[0:15]
	s_waitcnt lgkmcnt(0)
	v_mfma_f32_32x32x16_bf16 v[16:31], v[182:185], v[94:97], v[16:31]
	s_waitcnt vmcnt(0)
	s_barrier
	s_add_u32 s8, s8, 1
	s_cmp_lt_u32 s8, s9
	s_cbranch_scc1 .Lat_loop_0
	s_branch .Lat_epilogue
